# scan: wait per 4 steps with 8 register sets (prefetch 4), loads at head, deferred transposes, aligned loops
# baseline (speedup 1.0000x reference)
.LBB0_56:
	s_and_b64 s[4:5], s[42:43], exec
	s_mov_b32 s4, 0x1caf0000
	s_cselect_b32 s4, s4, 0x14af0000
	s_add_u32 s4, s30, s4
	s_addc_u32 s5, s31, 0
	s_lshl_b32 s6, s37, 1
	v_lshl_add_u32 v0, s64, 4, v58
	s_add_u32 s4, s4, s6
	s_addc_u32 s5, s5, 0
	v_ashrrev_i32_e32 v1, 31, v0
	s_waitcnt lgkmcnt(0)
	s_barrier
	v_lshl_add_u64 v[0:1], v[0:1], 1, s[4:5]
	s_and_b64 s[4:5], s[42:43], exec
	s_movk_i32 s4, 0x4000
	s_mov_b32 s28, 0
	s_cselect_b32 s85, 0, -1
	s_cselect_b32 s84, s4, 0xffffc000
	s_waitcnt vmcnt(0)
	v_mov_b32_e32 v6, 0
	v_mov_b32_e32 v4, v78
	v_mov_b32_e32 v5, v15
	v_mov_b32_e32 v7, 0
	v_mov_b32_e32 v8, 0
	v_mov_b32_e32 v9, 0
	v_lshlrev_b32_e32 v74, 4, v58
	v_add_u32_e32 v74, 0x22000, v74
	s_mov_b64 s[100:101], 0
	v_mov_b32_e32 v10, v59
	v_mov_b32_e32 v11, v74
	ds_read_b128 v[66:69], v11 offset:0
	ds_read_b128 v[20:23], v10 offset:256
	ds_read_b128 v[28:31], v10 offset:768
	ds_read_b128 v[24:27], v10 offset:512
	ds_read_b128 v[36:39], v10 offset:1280
	ds_read_b128 v[44:47], v10 offset:1792
	ds_read_b128 v[40:43], v10 offset:1536
	ds_read_b128 v[88:91], v10 offset:2304
	ds_read_b128 v[96:99], v10 offset:2816
	ds_read_b128 v[92:95], v10 offset:2560
	ds_read_b128 v[110:113], v10 offset:3328
	ds_read_b128 v[106:109], v10 offset:3072
	ds_read_b128 v[118:121], v10 offset:3840
	ds_read_b128 v[114:117], v10 offset:3584
.Lscan_cons_chunk:
	s_nop 0
	v_cndmask_b32_e64 v2, v4, v5, s[42:43]
	v_add_lshl_u32 v2, v2, s80, 10
	v_mov_b32_e64 v3, v180
	s_add_i32 s28, s28, 0x10000
	v_lshl_add_u64 v[2:3], v[0:1], 0, v[2:3]
	v_add_u32_e64 v5, 64, v5
	v_subrev_u32_e64 v4, 64, v4
	s_waitcnt lgkmcnt(0)
	s_nop 0
	ds_read_b128 v[142:145], v10 offset:4352
	ds_read_b128 v[150:153], v10 offset:4864
	ds_read_b128 v[146:149], v10 offset:4608
	v_fma_mix_f32 v12, v6, v20, v180 op_sel_hi:[0,1,0]
	v_fma_mix_f32 v12, v7, v20, v12 op_sel:[0,1,0] op_sel_hi:[0,1,0]
	v_fma_mix_f32 v12, v8, v21, v12 op_sel_hi:[0,1,0]
	v_fma_mix_f32 v12, v9, v21, v12 op_sel:[0,1,0] op_sel_hi:[0,1,0]
	s_nop 1
	s_nop 0
	v_add_f32_dpp v12, v12, v12 row_ror:1 row_mask:0xf bank_mask:0xf bound_ctrl:1
	s_nop 1
	s_nop 0
	v_add_f32_dpp v12, v12, v12 row_ror:2 row_mask:0xf bank_mask:0xf bound_ctrl:1
	v_pk_fma_f32 v[48:49], v[28:29], v[66:67], v[6:7] op_sel_hi:[1,0,1]
	v_pk_fma_f32 v[50:51], v[30:31], v[66:67], v[8:9] op_sel_hi:[1,0,1]
	v_add_f32_dpp v12, v12, v12 row_ror:4 row_mask:0xf bank_mask:0xf bound_ctrl:1
	v_add_f32_dpp v130, v130, v130 row_ror:8 row_mask:0xf bank_mask:0xc
	v_add_f32_dpp v130, v122, v122 row_ror:8 row_mask:0xf bank_mask:0x3
	v_add_f32_dpp v131, v131, v131 row_ror:8 row_mask:0xf bank_mask:0xc
	v_add_f32_dpp v12, v12, v12 row_ror:8 row_mask:0xf bank_mask:0xf bound_ctrl:1
	v_pk_fma_f32 v[6:7], v[24:25], v[12:13], v[48:49] op_sel_hi:[1,0,1] neg_lo:[1,0,0] neg_hi:[1,0,0]
	v_pk_fma_f32 v[8:9], v[26:27], v[12:13], v[50:51] op_sel_hi:[1,0,1] neg_lo:[1,0,0] neg_hi:[1,0,0]
	ds_read_b128 v[158:161], v10 offset:5376
	ds_read_b128 v[166:169], v10 offset:5888
	ds_read_b128 v[162:165], v10 offset:5632
	ds_read_b128 v[70:73], v11 offset:256
	v_fma_mix_f32 v12, v6, v36, v180 op_sel_hi:[0,1,0]
	v_fma_mix_f32 v12, v7, v36, v12 op_sel:[0,1,0] op_sel_hi:[0,1,0]
	v_fma_mix_f32 v12, v8, v37, v12 op_sel_hi:[0,1,0]
	v_fma_mix_f32 v12, v9, v37, v12 op_sel:[0,1,0] op_sel_hi:[0,1,0]
	v_fma_mix_f32 v52, v6, v22, v180 op_sel_hi:[0,1,0]
	v_fma_mix_f32 v52, v7, v22, v52 op_sel:[0,1,0] op_sel_hi:[0,1,0]
	v_add_f32_dpp v12, v12, v12 row_ror:1 row_mask:0xf bank_mask:0xf bound_ctrl:1
	v_fma_mix_f32 v52, v8, v23, v52 op_sel_hi:[0,1,0]
	v_fma_mix_f32 v52, v9, v23, v52 op_sel:[0,1,0] op_sel_hi:[0,1,0]
	v_add_f32_dpp v12, v12, v12 row_ror:2 row_mask:0xf bank_mask:0xf bound_ctrl:1
	v_pk_fma_f32 v[48:49], v[44:45], v[66:67], v[6:7] op_sel:[0,1,0]
	v_pk_fma_f32 v[50:51], v[46:47], v[66:67], v[8:9] op_sel:[0,1,0]
	v_add_f32_dpp v12, v12, v12 row_ror:4 row_mask:0xf bank_mask:0xf bound_ctrl:1
	v_add_f32_dpp v131, v123, v123 row_ror:8 row_mask:0xf bank_mask:0x3
	v_add_f32_dpp v132, v132, v132 row_ror:8 row_mask:0xf bank_mask:0xc
	v_add_f32_dpp v132, v124, v124 row_ror:8 row_mask:0xf bank_mask:0x3
	v_add_f32_dpp v12, v12, v12 row_ror:8 row_mask:0xf bank_mask:0xf bound_ctrl:1
	v_pk_fma_f32 v[6:7], v[40:41], v[12:13], v[48:49] op_sel_hi:[1,0,1] neg_lo:[1,0,0] neg_hi:[1,0,0]
	v_pk_fma_f32 v[8:9], v[42:43], v[12:13], v[50:51] op_sel_hi:[1,0,1] neg_lo:[1,0,0] neg_hi:[1,0,0]
	ds_read_b128 v[188:191], v10 offset:6400
	ds_read_b128 v[196:199], v10 offset:6912
	ds_read_b128 v[192:195], v10 offset:6656
	v_fma_mix_f32 v12, v6, v88, v180 op_sel_hi:[0,1,0]
	v_fma_mix_f32 v12, v7, v88, v12 op_sel:[0,1,0] op_sel_hi:[0,1,0]
	v_fma_mix_f32 v12, v8, v89, v12 op_sel_hi:[0,1,0]
	v_fma_mix_f32 v12, v9, v89, v12 op_sel:[0,1,0] op_sel_hi:[0,1,0]
	v_fma_mix_f32 v53, v6, v38, v180 op_sel_hi:[0,1,0]
	v_fma_mix_f32 v53, v7, v38, v53 op_sel:[0,1,0] op_sel_hi:[0,1,0]
	v_add_f32_dpp v12, v12, v12 row_ror:1 row_mask:0xf bank_mask:0xf bound_ctrl:1
	v_fma_mix_f32 v53, v8, v39, v53 op_sel_hi:[0,1,0]
	v_fma_mix_f32 v53, v9, v39, v53 op_sel:[0,1,0] op_sel_hi:[0,1,0]
	v_add_f32_dpp v12, v12, v12 row_ror:2 row_mask:0xf bank_mask:0xf bound_ctrl:1
	v_pk_fma_f32 v[48:49], v[96:97], v[68:69], v[6:7] op_sel_hi:[1,0,1]
	v_pk_fma_f32 v[50:51], v[98:99], v[68:69], v[8:9] op_sel_hi:[1,0,1]
	v_add_f32_dpp v12, v12, v12 row_ror:4 row_mask:0xf bank_mask:0xf bound_ctrl:1
	v_add_f32_dpp v133, v133, v133 row_ror:8 row_mask:0xf bank_mask:0xc
	v_add_f32_dpp v133, v125, v125 row_ror:8 row_mask:0xf bank_mask:0x3
	v_add_f32_dpp v134, v134, v134 row_ror:8 row_mask:0xf bank_mask:0xc
	v_add_f32_dpp v12, v12, v12 row_ror:8 row_mask:0xf bank_mask:0xf bound_ctrl:1
	v_pk_fma_f32 v[6:7], v[92:93], v[12:13], v[48:49] op_sel_hi:[1,0,1] neg_lo:[1,0,0] neg_hi:[1,0,0]
	v_pk_fma_f32 v[8:9], v[94:95], v[12:13], v[50:51] op_sel_hi:[1,0,1] neg_lo:[1,0,0] neg_hi:[1,0,0]
	ds_read_b128 v[204:207], v10 offset:7424
	ds_read_b128 v[200:203], v10 offset:7168
	ds_read_b128 v[212:215], v10 offset:7936
	ds_read_b128 v[208:211], v10 offset:7680
	v_fma_mix_f32 v12, v6, v110, v180 op_sel_hi:[0,1,0]
	v_fma_mix_f32 v12, v7, v110, v12 op_sel:[0,1,0] op_sel_hi:[0,1,0]
	v_fma_mix_f32 v12, v8, v111, v12 op_sel_hi:[0,1,0]
	v_fma_mix_f32 v12, v9, v111, v12 op_sel:[0,1,0] op_sel_hi:[0,1,0]
	v_fma_mix_f32 v54, v6, v90, v180 op_sel_hi:[0,1,0]
	v_fma_mix_f32 v54, v7, v90, v54 op_sel:[0,1,0] op_sel_hi:[0,1,0]
	v_add_f32_dpp v12, v12, v12 row_ror:1 row_mask:0xf bank_mask:0xf bound_ctrl:1
	v_fma_mix_f32 v54, v8, v91, v54 op_sel_hi:[0,1,0]
	v_fma_mix_f32 v54, v9, v91, v54 op_sel:[0,1,0] op_sel_hi:[0,1,0]
	v_add_f32_dpp v12, v12, v12 row_ror:2 row_mask:0xf bank_mask:0xf bound_ctrl:1
	v_pk_fma_f32 v[48:49], v[118:119], v[68:69], v[6:7] op_sel:[0,1,0]
	v_pk_fma_f32 v[50:51], v[120:121], v[68:69], v[8:9] op_sel:[0,1,0]
	v_add_f32_dpp v12, v12, v12 row_ror:4 row_mask:0xf bank_mask:0xf bound_ctrl:1
	v_add_f32_dpp v134, v126, v126 row_ror:8 row_mask:0xf bank_mask:0x3
	v_add_f32_dpp v135, v135, v135 row_ror:8 row_mask:0xf bank_mask:0xc
	v_add_f32_dpp v135, v127, v127 row_ror:8 row_mask:0xf bank_mask:0x3
	v_add_f32_dpp v12, v12, v12 row_ror:8 row_mask:0xf bank_mask:0xf bound_ctrl:1
	v_pk_fma_f32 v[6:7], v[114:115], v[12:13], v[48:49] op_sel_hi:[1,0,1] neg_lo:[1,0,0] neg_hi:[1,0,0]
	v_pk_fma_f32 v[8:9], v[116:117], v[12:13], v[50:51] op_sel_hi:[1,0,1] neg_lo:[1,0,0] neg_hi:[1,0,0]
	v_pk_mul_f32 v[6:7], v[6:7], v[106:107]
	v_pk_mul_f32 v[8:9], v[8:9], v[108:109]
	s_waitcnt lgkmcnt(0)
	s_nop 0
	ds_read_b128 v[20:23], v10 offset:8448
	ds_read_b128 v[28:31], v10 offset:8960
	ds_read_b128 v[24:27], v10 offset:8704
	v_fma_mix_f32 v12, v6, v142, v180 op_sel_hi:[0,1,0]
	v_fma_mix_f32 v12, v7, v142, v12 op_sel:[0,1,0] op_sel_hi:[0,1,0]
	v_fma_mix_f32 v12, v8, v143, v12 op_sel_hi:[0,1,0]
	v_fma_mix_f32 v12, v9, v143, v12 op_sel:[0,1,0] op_sel_hi:[0,1,0]
	v_fma_mix_f32 v55, v6, v112, v180 op_sel_hi:[0,1,0]
	v_fma_mix_f32 v55, v7, v112, v55 op_sel:[0,1,0] op_sel_hi:[0,1,0]
	v_add_f32_dpp v12, v12, v12 row_ror:1 row_mask:0xf bank_mask:0xf bound_ctrl:1
	v_fma_mix_f32 v55, v8, v113, v55 op_sel_hi:[0,1,0]
	v_fma_mix_f32 v55, v9, v113, v55 op_sel:[0,1,0] op_sel_hi:[0,1,0]
	v_add_f32_dpp v12, v12, v12 row_ror:2 row_mask:0xf bank_mask:0xf bound_ctrl:1
	v_pk_fma_f32 v[48:49], v[150:151], v[70:71], v[6:7] op_sel_hi:[1,0,1]
	v_pk_fma_f32 v[50:51], v[152:153], v[70:71], v[8:9] op_sel_hi:[1,0,1]
	v_add_f32_dpp v12, v12, v12 row_ror:4 row_mask:0xf bank_mask:0xf bound_ctrl:1
	v_add_f32_dpp v136, v136, v136 row_ror:8 row_mask:0xf bank_mask:0xc
	v_add_f32_dpp v136, v128, v128 row_ror:8 row_mask:0xf bank_mask:0x3
	v_add_f32_dpp v12, v12, v12 row_ror:8 row_mask:0xf bank_mask:0xf bound_ctrl:1
	v_pk_fma_f32 v[6:7], v[146:147], v[12:13], v[48:49] op_sel_hi:[1,0,1] neg_lo:[1,0,0] neg_hi:[1,0,0]
	v_pk_fma_f32 v[8:9], v[148:149], v[12:13], v[50:51] op_sel_hi:[1,0,1] neg_lo:[1,0,0] neg_hi:[1,0,0]
	ds_read_b128 v[36:39], v10 offset:9472
	ds_read_b128 v[44:47], v10 offset:9984
	ds_read_b128 v[40:43], v10 offset:9728
	ds_read_b128 v[66:69], v11 offset:512
	v_fma_mix_f32 v12, v6, v158, v180 op_sel_hi:[0,1,0]
	v_fma_mix_f32 v12, v7, v158, v12 op_sel:[0,1,0] op_sel_hi:[0,1,0]
	v_fma_mix_f32 v12, v8, v159, v12 op_sel_hi:[0,1,0]
	v_fma_mix_f32 v12, v9, v159, v12 op_sel:[0,1,0] op_sel_hi:[0,1,0]
	v_fma_mix_f32 v56, v6, v144, v180 op_sel_hi:[0,1,0]
	v_fma_mix_f32 v56, v7, v144, v56 op_sel:[0,1,0] op_sel_hi:[0,1,0]
	v_add_f32_dpp v12, v12, v12 row_ror:1 row_mask:0xf bank_mask:0xf bound_ctrl:1
	v_fma_mix_f32 v56, v8, v145, v56 op_sel_hi:[0,1,0]
	v_fma_mix_f32 v56, v9, v145, v56 op_sel:[0,1,0] op_sel_hi:[0,1,0]
	v_add_f32_dpp v12, v12, v12 row_ror:2 row_mask:0xf bank_mask:0xf bound_ctrl:1
	v_pk_fma_f32 v[48:49], v[166:167], v[70:71], v[6:7] op_sel:[0,1,0]
	v_pk_fma_f32 v[50:51], v[168:169], v[70:71], v[8:9] op_sel:[0,1,0]
	v_add_f32_dpp v12, v12, v12 row_ror:4 row_mask:0xf bank_mask:0xf bound_ctrl:1
	v_add_f32_dpp v137, v137, v137 row_ror:8 row_mask:0xf bank_mask:0xc
	v_add_f32_dpp v137, v129, v129 row_ror:8 row_mask:0xf bank_mask:0x3
	v_add_f32_dpp v12, v12, v12 row_ror:8 row_mask:0xf bank_mask:0xf bound_ctrl:1
	v_pk_fma_f32 v[6:7], v[162:163], v[12:13], v[48:49] op_sel_hi:[1,0,1] neg_lo:[1,0,0] neg_hi:[1,0,0]
	v_pk_fma_f32 v[8:9], v[164:165], v[12:13], v[50:51] op_sel_hi:[1,0,1] neg_lo:[1,0,0] neg_hi:[1,0,0]
	ds_read_b128 v[88:91], v10 offset:10496
	ds_read_b128 v[96:99], v10 offset:11008
	ds_read_b128 v[92:95], v10 offset:10752
	v_fma_mix_f32 v12, v6, v188, v180 op_sel_hi:[0,1,0]
	v_fma_mix_f32 v12, v7, v188, v12 op_sel:[0,1,0] op_sel_hi:[0,1,0]
	v_fma_mix_f32 v12, v8, v189, v12 op_sel_hi:[0,1,0]
	v_fma_mix_f32 v12, v9, v189, v12 op_sel:[0,1,0] op_sel_hi:[0,1,0]
	v_fma_mix_f32 v57, v6, v160, v180 op_sel_hi:[0,1,0]
	v_fma_mix_f32 v57, v7, v160, v57 op_sel:[0,1,0] op_sel_hi:[0,1,0]
	v_add_f32_dpp v12, v12, v12 row_ror:1 row_mask:0xf bank_mask:0xf bound_ctrl:1
	v_fma_mix_f32 v57, v8, v161, v57 op_sel_hi:[0,1,0]
	v_fma_mix_f32 v57, v9, v161, v57 op_sel:[0,1,0] op_sel_hi:[0,1,0]
	v_add_f32_dpp v12, v12, v12 row_ror:2 row_mask:0xf bank_mask:0xf bound_ctrl:1
	v_pk_fma_f32 v[48:49], v[196:197], v[72:73], v[6:7] op_sel_hi:[1,0,1]
	v_pk_fma_f32 v[50:51], v[198:199], v[72:73], v[8:9] op_sel_hi:[1,0,1]
	v_add_f32_dpp v12, v12, v12 row_ror:4 row_mask:0xf bank_mask:0xf bound_ctrl:1
	v_add_f32_dpp v134, v134, v134 row_ror:4 row_mask:0xf bank_mask:0xa
	v_add_f32_dpp v134, v130, v130 row_ror:12 row_mask:0xf bank_mask:0x5
	v_add_f32_dpp v135, v135, v135 row_ror:4 row_mask:0xf bank_mask:0xa
	v_add_f32_dpp v12, v12, v12 row_ror:8 row_mask:0xf bank_mask:0xf bound_ctrl:1
	v_pk_fma_f32 v[6:7], v[192:193], v[12:13], v[48:49] op_sel_hi:[1,0,1] neg_lo:[1,0,0] neg_hi:[1,0,0]
	v_pk_fma_f32 v[8:9], v[194:195], v[12:13], v[50:51] op_sel_hi:[1,0,1] neg_lo:[1,0,0] neg_hi:[1,0,0]
	ds_read_b128 v[110:113], v10 offset:11520
	ds_read_b128 v[106:109], v10 offset:11264
	ds_read_b128 v[118:121], v10 offset:12032
	ds_read_b128 v[114:117], v10 offset:11776
	v_fma_mix_f32 v12, v6, v204, v180 op_sel_hi:[0,1,0]
	v_fma_mix_f32 v12, v7, v204, v12 op_sel:[0,1,0] op_sel_hi:[0,1,0]
	v_fma_mix_f32 v12, v8, v205, v12 op_sel_hi:[0,1,0]
	v_fma_mix_f32 v12, v9, v205, v12 op_sel:[0,1,0] op_sel_hi:[0,1,0]
	v_fma_mix_f32 v81, v6, v190, v180 op_sel_hi:[0,1,0]
	v_fma_mix_f32 v81, v7, v190, v81 op_sel:[0,1,0] op_sel_hi:[0,1,0]
	v_add_f32_dpp v12, v12, v12 row_ror:1 row_mask:0xf bank_mask:0xf bound_ctrl:1
	v_fma_mix_f32 v81, v8, v191, v81 op_sel_hi:[0,1,0]
	v_fma_mix_f32 v81, v9, v191, v81 op_sel:[0,1,0] op_sel_hi:[0,1,0]
	v_add_f32_dpp v12, v12, v12 row_ror:2 row_mask:0xf bank_mask:0xf bound_ctrl:1
	v_pk_fma_f32 v[48:49], v[212:213], v[72:73], v[6:7] op_sel:[0,1,0]
	v_pk_fma_f32 v[50:51], v[214:215], v[72:73], v[8:9] op_sel:[0,1,0]
	v_add_f32_dpp v12, v12, v12 row_ror:4 row_mask:0xf bank_mask:0xf bound_ctrl:1
	v_add_f32_dpp v135, v131, v131 row_ror:12 row_mask:0xf bank_mask:0x5
	v_add_f32_dpp v136, v136, v136 row_ror:4 row_mask:0xf bank_mask:0xa
	v_add_f32_dpp v136, v132, v132 row_ror:12 row_mask:0xf bank_mask:0x5
	v_add_f32_dpp v12, v12, v12 row_ror:8 row_mask:0xf bank_mask:0xf bound_ctrl:1
	v_pk_fma_f32 v[6:7], v[208:209], v[12:13], v[48:49] op_sel_hi:[1,0,1] neg_lo:[1,0,0] neg_hi:[1,0,0]
	v_pk_fma_f32 v[8:9], v[210:211], v[12:13], v[50:51] op_sel_hi:[1,0,1] neg_lo:[1,0,0] neg_hi:[1,0,0]
	v_pk_mul_f32 v[6:7], v[6:7], v[200:201]
	v_pk_mul_f32 v[8:9], v[8:9], v[202:203]
	s_waitcnt lgkmcnt(0)
	s_nop 0
	ds_read_b128 v[142:145], v10 offset:12544
	ds_read_b128 v[150:153], v10 offset:13056
	ds_read_b128 v[146:149], v10 offset:12800
	v_fma_mix_f32 v12, v6, v20, v180 op_sel_hi:[0,1,0]
	v_fma_mix_f32 v12, v7, v20, v12 op_sel:[0,1,0] op_sel_hi:[0,1,0]
	v_fma_mix_f32 v12, v8, v21, v12 op_sel_hi:[0,1,0]
	v_fma_mix_f32 v12, v9, v21, v12 op_sel:[0,1,0] op_sel_hi:[0,1,0]
	v_fma_mix_f32 v82, v6, v206, v180 op_sel_hi:[0,1,0]
	v_fma_mix_f32 v82, v7, v206, v82 op_sel:[0,1,0] op_sel_hi:[0,1,0]
	v_add_f32_dpp v12, v12, v12 row_ror:1 row_mask:0xf bank_mask:0xf bound_ctrl:1
	v_fma_mix_f32 v82, v8, v207, v82 op_sel_hi:[0,1,0]
	v_fma_mix_f32 v82, v9, v207, v82 op_sel:[0,1,0] op_sel_hi:[0,1,0]
	v_add_f32_dpp v12, v12, v12 row_ror:2 row_mask:0xf bank_mask:0xf bound_ctrl:1
	v_pk_fma_f32 v[48:49], v[28:29], v[66:67], v[6:7] op_sel_hi:[1,0,1]
	v_pk_fma_f32 v[50:51], v[30:31], v[66:67], v[8:9] op_sel_hi:[1,0,1]
	v_add_f32_dpp v12, v12, v12 row_ror:4 row_mask:0xf bank_mask:0xf bound_ctrl:1
	v_add_f32_dpp v137, v137, v137 row_ror:4 row_mask:0xf bank_mask:0xa
	v_add_f32_dpp v137, v133, v133 row_ror:12 row_mask:0xf bank_mask:0x5
	v_add_f32_dpp v12, v12, v12 row_ror:8 row_mask:0xf bank_mask:0xf bound_ctrl:1
	v_pk_fma_f32 v[6:7], v[24:25], v[12:13], v[48:49] op_sel_hi:[1,0,1] neg_lo:[1,0,0] neg_hi:[1,0,0]
	v_pk_fma_f32 v[8:9], v[26:27], v[12:13], v[50:51] op_sel_hi:[1,0,1] neg_lo:[1,0,0] neg_hi:[1,0,0]
	ds_read_b128 v[158:161], v10 offset:13568
	ds_read_b128 v[166:169], v10 offset:14080
	ds_read_b128 v[162:165], v10 offset:13824
	ds_read_b128 v[70:73], v11 offset:768
	v_fma_mix_f32 v12, v6, v36, v180 op_sel_hi:[0,1,0]
	v_fma_mix_f32 v12, v7, v36, v12 op_sel:[0,1,0] op_sel_hi:[0,1,0]
	v_fma_mix_f32 v12, v8, v37, v12 op_sel_hi:[0,1,0]
	v_fma_mix_f32 v12, v9, v37, v12 op_sel:[0,1,0] op_sel_hi:[0,1,0]
	v_fma_mix_f32 v83, v6, v22, v180 op_sel_hi:[0,1,0]
	v_fma_mix_f32 v83, v7, v22, v83 op_sel:[0,1,0] op_sel_hi:[0,1,0]
	v_add_f32_dpp v12, v12, v12 row_ror:1 row_mask:0xf bank_mask:0xf bound_ctrl:1
	v_fma_mix_f32 v83, v8, v23, v83 op_sel_hi:[0,1,0]
	v_fma_mix_f32 v83, v9, v23, v83 op_sel:[0,1,0] op_sel_hi:[0,1,0]
	v_add_f32_dpp v12, v12, v12 row_ror:2 row_mask:0xf bank_mask:0xf bound_ctrl:1
	v_pk_fma_f32 v[48:49], v[44:45], v[66:67], v[6:7] op_sel:[0,1,0]
	v_pk_fma_f32 v[50:51], v[46:47], v[66:67], v[8:9] op_sel:[0,1,0]
	v_add_f32_dpp v12, v12, v12 row_ror:4 row_mask:0xf bank_mask:0xf bound_ctrl:1
	v_cndmask_b32_e64 v62, v136, v134, s[38:39]
	v_cndmask_b32_e64 v63, v134, v136, s[38:39]
	v_add_f32_dpp v12, v12, v12 row_ror:8 row_mask:0xf bank_mask:0xf bound_ctrl:1
	v_pk_fma_f32 v[6:7], v[40:41], v[12:13], v[48:49] op_sel_hi:[1,0,1] neg_lo:[1,0,0] neg_hi:[1,0,0]
	v_pk_fma_f32 v[8:9], v[42:43], v[12:13], v[50:51] op_sel_hi:[1,0,1] neg_lo:[1,0,0] neg_hi:[1,0,0]
	ds_read_b128 v[188:191], v10 offset:14592
	ds_read_b128 v[196:199], v10 offset:15104
	ds_read_b128 v[192:195], v10 offset:14848
	v_fma_mix_f32 v12, v6, v88, v180 op_sel_hi:[0,1,0]
	v_fma_mix_f32 v12, v7, v88, v12 op_sel:[0,1,0] op_sel_hi:[0,1,0]
	v_fma_mix_f32 v12, v8, v89, v12 op_sel_hi:[0,1,0]
	v_fma_mix_f32 v12, v9, v89, v12 op_sel:[0,1,0] op_sel_hi:[0,1,0]
	v_fma_mix_f32 v100, v6, v38, v180 op_sel_hi:[0,1,0]
	v_fma_mix_f32 v100, v7, v38, v100 op_sel:[0,1,0] op_sel_hi:[0,1,0]
	v_add_f32_dpp v12, v12, v12 row_ror:1 row_mask:0xf bank_mask:0xf bound_ctrl:1
	v_fma_mix_f32 v100, v8, v39, v100 op_sel_hi:[0,1,0]
	v_fma_mix_f32 v100, v9, v39, v100 op_sel:[0,1,0] op_sel_hi:[0,1,0]
	v_add_f32_dpp v12, v12, v12 row_ror:2 row_mask:0xf bank_mask:0xf bound_ctrl:1
	v_pk_fma_f32 v[48:49], v[96:97], v[68:69], v[6:7] op_sel_hi:[1,0,1]
	v_pk_fma_f32 v[50:51], v[98:99], v[68:69], v[8:9] op_sel_hi:[1,0,1]
	v_add_f32_dpp v12, v12, v12 row_ror:4 row_mask:0xf bank_mask:0xf bound_ctrl:1
	v_cndmask_b32_e64 v64, v137, v135, s[38:39]
	v_cndmask_b32_e64 v65, v135, v137, s[38:39]
	v_add_f32_dpp v12, v12, v12 row_ror:8 row_mask:0xf bank_mask:0xf bound_ctrl:1
	v_pk_fma_f32 v[6:7], v[92:93], v[12:13], v[48:49] op_sel_hi:[1,0,1] neg_lo:[1,0,0] neg_hi:[1,0,0]
	v_pk_fma_f32 v[8:9], v[94:95], v[12:13], v[50:51] op_sel_hi:[1,0,1] neg_lo:[1,0,0] neg_hi:[1,0,0]
	ds_read_b128 v[204:207], v10 offset:15616
	ds_read_b128 v[200:203], v10 offset:15360
	ds_read_b128 v[212:215], v10 offset:16128
	ds_read_b128 v[208:211], v10 offset:15872
	v_fma_mix_f32 v12, v6, v110, v180 op_sel_hi:[0,1,0]
	v_fma_mix_f32 v12, v7, v110, v12 op_sel:[0,1,0] op_sel_hi:[0,1,0]
	v_fma_mix_f32 v12, v8, v111, v12 op_sel_hi:[0,1,0]
	v_fma_mix_f32 v12, v9, v111, v12 op_sel:[0,1,0] op_sel_hi:[0,1,0]
	v_fma_mix_f32 v101, v6, v90, v180 op_sel_hi:[0,1,0]
	v_fma_mix_f32 v101, v7, v90, v101 op_sel:[0,1,0] op_sel_hi:[0,1,0]
	v_add_f32_dpp v12, v12, v12 row_ror:1 row_mask:0xf bank_mask:0xf bound_ctrl:1
	v_fma_mix_f32 v101, v8, v91, v101 op_sel_hi:[0,1,0]
	v_fma_mix_f32 v101, v9, v91, v101 op_sel:[0,1,0] op_sel_hi:[0,1,0]
	v_add_f32_dpp v12, v12, v12 row_ror:2 row_mask:0xf bank_mask:0xf bound_ctrl:1
	v_pk_fma_f32 v[48:49], v[118:119], v[68:69], v[6:7] op_sel:[0,1,0]
	v_pk_fma_f32 v[50:51], v[120:121], v[68:69], v[8:9] op_sel:[0,1,0]
	v_add_f32_dpp v12, v12, v12 row_ror:4 row_mask:0xf bank_mask:0xf bound_ctrl:1
	v_add_f32_dpp v62, v63, v62 quad_perm:[2,3,0,1] row_mask:0xf bank_mask:0xf bound_ctrl:1
	v_add_f32_dpp v63, v65, v64 quad_perm:[2,3,0,1] row_mask:0xf bank_mask:0xf bound_ctrl:1
	v_add_f32_dpp v12, v12, v12 row_ror:8 row_mask:0xf bank_mask:0xf bound_ctrl:1
	v_pk_fma_f32 v[6:7], v[114:115], v[12:13], v[48:49] op_sel_hi:[1,0,1] neg_lo:[1,0,0] neg_hi:[1,0,0]
	v_pk_fma_f32 v[8:9], v[116:117], v[12:13], v[50:51] op_sel_hi:[1,0,1] neg_lo:[1,0,0] neg_hi:[1,0,0]
	v_pk_mul_f32 v[6:7], v[6:7], v[106:107]
	v_pk_mul_f32 v[8:9], v[8:9], v[108:109]
	s_waitcnt lgkmcnt(0)
	s_nop 0
	ds_read_b128 v[20:23], v10 offset:16640
	ds_read_b128 v[28:31], v10 offset:17152
	ds_read_b128 v[24:27], v10 offset:16896
	v_fma_mix_f32 v12, v6, v142, v180 op_sel_hi:[0,1,0]
	v_fma_mix_f32 v12, v7, v142, v12 op_sel:[0,1,0] op_sel_hi:[0,1,0]
	v_fma_mix_f32 v12, v8, v143, v12 op_sel_hi:[0,1,0]
	v_fma_mix_f32 v12, v9, v143, v12 op_sel:[0,1,0] op_sel_hi:[0,1,0]
	v_fma_mix_f32 v102, v6, v112, v180 op_sel_hi:[0,1,0]
	v_fma_mix_f32 v102, v7, v112, v102 op_sel:[0,1,0] op_sel_hi:[0,1,0]
	v_add_f32_dpp v12, v12, v12 row_ror:1 row_mask:0xf bank_mask:0xf bound_ctrl:1
	v_fma_mix_f32 v102, v8, v113, v102 op_sel_hi:[0,1,0]
	v_fma_mix_f32 v102, v9, v113, v102 op_sel:[0,1,0] op_sel_hi:[0,1,0]
	v_add_f32_dpp v12, v12, v12 row_ror:2 row_mask:0xf bank_mask:0xf bound_ctrl:1
	v_pk_fma_f32 v[48:49], v[150:151], v[70:71], v[6:7] op_sel_hi:[1,0,1]
	v_pk_fma_f32 v[50:51], v[152:153], v[70:71], v[8:9] op_sel_hi:[1,0,1]
	v_add_f32_dpp v12, v12, v12 row_ror:4 row_mask:0xf bank_mask:0xf bound_ctrl:1
	v_cndmask_b32_e64 v65, v63, v62, s[40:41]
	v_cndmask_b32_e64 v62, v62, v63, s[40:41]
	v_add_f32_dpp v12, v12, v12 row_ror:8 row_mask:0xf bank_mask:0xf bound_ctrl:1
	v_pk_fma_f32 v[6:7], v[146:147], v[12:13], v[48:49] op_sel_hi:[1,0,1] neg_lo:[1,0,0] neg_hi:[1,0,0]
	v_pk_fma_f32 v[8:9], v[148:149], v[12:13], v[50:51] op_sel_hi:[1,0,1] neg_lo:[1,0,0] neg_hi:[1,0,0]
	ds_read_b128 v[36:39], v10 offset:17664
	ds_read_b128 v[44:47], v10 offset:18176
	ds_read_b128 v[40:43], v10 offset:17920
	ds_read_b128 v[66:69], v11 offset:1024
	v_fma_mix_f32 v12, v6, v158, v180 op_sel_hi:[0,1,0]
	v_fma_mix_f32 v12, v7, v158, v12 op_sel:[0,1,0] op_sel_hi:[0,1,0]
	v_fma_mix_f32 v12, v8, v159, v12 op_sel_hi:[0,1,0]
	v_fma_mix_f32 v12, v9, v159, v12 op_sel:[0,1,0] op_sel_hi:[0,1,0]
	v_fma_mix_f32 v103, v6, v144, v180 op_sel_hi:[0,1,0]
	v_fma_mix_f32 v103, v7, v144, v103 op_sel:[0,1,0] op_sel_hi:[0,1,0]
	v_add_f32_dpp v12, v12, v12 row_ror:1 row_mask:0xf bank_mask:0xf bound_ctrl:1
	v_fma_mix_f32 v103, v8, v145, v103 op_sel_hi:[0,1,0]
	v_fma_mix_f32 v103, v9, v145, v103 op_sel:[0,1,0] op_sel_hi:[0,1,0]
	v_add_f32_dpp v12, v12, v12 row_ror:2 row_mask:0xf bank_mask:0xf bound_ctrl:1
	v_pk_fma_f32 v[48:49], v[166:167], v[70:71], v[6:7] op_sel:[0,1,0]
	v_pk_fma_f32 v[50:51], v[168:169], v[70:71], v[8:9] op_sel:[0,1,0]
	v_add_f32_dpp v12, v12, v12 row_ror:4 row_mask:0xf bank_mask:0xf bound_ctrl:1
	v_add_f32_dpp v62, v62, v65 quad_perm:[1,0,3,2] row_mask:0xf bank_mask:0xf bound_ctrl:1
	v_cvt_pk_bf16_f32 v62, v62, v62
	v_add_f32_dpp v12, v12, v12 row_ror:8 row_mask:0xf bank_mask:0xf bound_ctrl:1
	v_pk_fma_f32 v[6:7], v[162:163], v[12:13], v[48:49] op_sel_hi:[1,0,1] neg_lo:[1,0,0] neg_hi:[1,0,0]
	v_pk_fma_f32 v[8:9], v[164:165], v[12:13], v[50:51] op_sel_hi:[1,0,1] neg_lo:[1,0,0] neg_hi:[1,0,0]
	ds_read_b128 v[88:91], v10 offset:18688
	ds_read_b128 v[96:99], v10 offset:19200
	ds_read_b128 v[92:95], v10 offset:18944
	v_fma_mix_f32 v12, v6, v188, v180 op_sel_hi:[0,1,0]
	v_fma_mix_f32 v12, v7, v188, v12 op_sel:[0,1,0] op_sel_hi:[0,1,0]
	v_fma_mix_f32 v12, v8, v189, v12 op_sel_hi:[0,1,0]
	v_fma_mix_f32 v12, v9, v189, v12 op_sel:[0,1,0] op_sel_hi:[0,1,0]
	v_fma_mix_f32 v104, v6, v160, v180 op_sel_hi:[0,1,0]
	v_fma_mix_f32 v104, v7, v160, v104 op_sel:[0,1,0] op_sel_hi:[0,1,0]
	v_add_f32_dpp v12, v12, v12 row_ror:1 row_mask:0xf bank_mask:0xf bound_ctrl:1
	v_fma_mix_f32 v104, v8, v161, v104 op_sel_hi:[0,1,0]
	v_fma_mix_f32 v104, v9, v161, v104 op_sel:[0,1,0] op_sel_hi:[0,1,0]
	v_add_f32_dpp v12, v12, v12 row_ror:2 row_mask:0xf bank_mask:0xf bound_ctrl:1
	v_pk_fma_f32 v[48:49], v[196:197], v[72:73], v[6:7] op_sel_hi:[1,0,1]
	v_pk_fma_f32 v[50:51], v[198:199], v[72:73], v[8:9] op_sel_hi:[1,0,1]
	v_add_f32_dpp v12, v12, v12 row_ror:4 row_mask:0xf bank_mask:0xf bound_ctrl:1
	s_mov_b64 exec, s[100:101]
	s_nop 0
	global_store_short v[170:171], v62, off
	s_mov_b64 exec, -1
	s_nop 0
	v_add_f32_dpp v12, v12, v12 row_ror:8 row_mask:0xf bank_mask:0xf bound_ctrl:1
	v_pk_fma_f32 v[6:7], v[192:193], v[12:13], v[48:49] op_sel_hi:[1,0,1] neg_lo:[1,0,0] neg_hi:[1,0,0]
	v_pk_fma_f32 v[8:9], v[194:195], v[12:13], v[50:51] op_sel_hi:[1,0,1] neg_lo:[1,0,0] neg_hi:[1,0,0]
	ds_read_b128 v[110:113], v10 offset:19712
	ds_read_b128 v[106:109], v10 offset:19456
	ds_read_b128 v[118:121], v10 offset:20224
	ds_read_b128 v[114:117], v10 offset:19968
	v_fma_mix_f32 v12, v6, v204, v180 op_sel_hi:[0,1,0]
	v_fma_mix_f32 v12, v7, v204, v12 op_sel:[0,1,0] op_sel_hi:[0,1,0]
	v_fma_mix_f32 v12, v8, v205, v12 op_sel_hi:[0,1,0]
	v_fma_mix_f32 v12, v9, v205, v12 op_sel:[0,1,0] op_sel_hi:[0,1,0]
	v_fma_mix_f32 v105, v6, v190, v180 op_sel_hi:[0,1,0]
	v_fma_mix_f32 v105, v7, v190, v105 op_sel:[0,1,0] op_sel_hi:[0,1,0]
	v_add_f32_dpp v12, v12, v12 row_ror:1 row_mask:0xf bank_mask:0xf bound_ctrl:1
	v_fma_mix_f32 v105, v8, v191, v105 op_sel_hi:[0,1,0]
	v_fma_mix_f32 v105, v9, v191, v105 op_sel:[0,1,0] op_sel_hi:[0,1,0]
	v_add_f32_dpp v12, v12, v12 row_ror:2 row_mask:0xf bank_mask:0xf bound_ctrl:1
	v_pk_fma_f32 v[48:49], v[212:213], v[72:73], v[6:7] op_sel:[0,1,0]
	v_pk_fma_f32 v[50:51], v[214:215], v[72:73], v[8:9] op_sel:[0,1,0]
	v_add_f32_dpp v12, v12, v12 row_ror:4 row_mask:0xf bank_mask:0xf bound_ctrl:1
	s_nop 1
	s_nop 0
	v_add_f32_dpp v12, v12, v12 row_ror:8 row_mask:0xf bank_mask:0xf bound_ctrl:1
	v_pk_fma_f32 v[6:7], v[208:209], v[12:13], v[48:49] op_sel_hi:[1,0,1] neg_lo:[1,0,0] neg_hi:[1,0,0]
	v_pk_fma_f32 v[8:9], v[210:211], v[12:13], v[50:51] op_sel_hi:[1,0,1] neg_lo:[1,0,0] neg_hi:[1,0,0]
	v_pk_mul_f32 v[6:7], v[6:7], v[200:201]
	v_pk_mul_f32 v[8:9], v[8:9], v[202:203]
	s_waitcnt lgkmcnt(0)
	s_nop 0
	ds_read_b128 v[142:145], v10 offset:20736
	ds_read_b128 v[150:153], v10 offset:21248
	ds_read_b128 v[146:149], v10 offset:20992
	v_fma_mix_f32 v12, v6, v20, v180 op_sel_hi:[0,1,0]
	v_fma_mix_f32 v12, v7, v20, v12 op_sel:[0,1,0] op_sel_hi:[0,1,0]
	v_fma_mix_f32 v12, v8, v21, v12 op_sel_hi:[0,1,0]
	v_fma_mix_f32 v12, v9, v21, v12 op_sel:[0,1,0] op_sel_hi:[0,1,0]
	v_fma_mix_f32 v61, v6, v206, v180 op_sel_hi:[0,1,0]
	v_fma_mix_f32 v61, v7, v206, v61 op_sel:[0,1,0] op_sel_hi:[0,1,0]
	v_add_f32_dpp v12, v12, v12 row_ror:1 row_mask:0xf bank_mask:0xf bound_ctrl:1
	v_fma_mix_f32 v61, v8, v207, v61 op_sel_hi:[0,1,0]
	v_fma_mix_f32 v61, v9, v207, v61 op_sel:[0,1,0] op_sel_hi:[0,1,0]
	v_add_f32_dpp v12, v12, v12 row_ror:2 row_mask:0xf bank_mask:0xf bound_ctrl:1
	v_pk_fma_f32 v[48:49], v[28:29], v[66:67], v[6:7] op_sel_hi:[1,0,1]
	v_pk_fma_f32 v[50:51], v[30:31], v[66:67], v[8:9] op_sel_hi:[1,0,1]
	v_add_f32_dpp v12, v12, v12 row_ror:4 row_mask:0xf bank_mask:0xf bound_ctrl:1
	s_nop 1
	s_nop 0
	v_add_f32_dpp v12, v12, v12 row_ror:8 row_mask:0xf bank_mask:0xf bound_ctrl:1
	v_pk_fma_f32 v[6:7], v[24:25], v[12:13], v[48:49] op_sel_hi:[1,0,1] neg_lo:[1,0,0] neg_hi:[1,0,0]
	v_pk_fma_f32 v[8:9], v[26:27], v[12:13], v[50:51] op_sel_hi:[1,0,1] neg_lo:[1,0,0] neg_hi:[1,0,0]
	ds_read_b128 v[158:161], v10 offset:21760
	ds_read_b128 v[166:169], v10 offset:22272
	ds_read_b128 v[162:165], v10 offset:22016
	ds_read_b128 v[70:73], v11 offset:1280
	v_fma_mix_f32 v12, v6, v36, v180 op_sel_hi:[0,1,0]
	v_fma_mix_f32 v12, v7, v36, v12 op_sel:[0,1,0] op_sel_hi:[0,1,0]
	v_fma_mix_f32 v12, v8, v37, v12 op_sel_hi:[0,1,0]
	v_fma_mix_f32 v12, v9, v37, v12 op_sel:[0,1,0] op_sel_hi:[0,1,0]
	v_fma_mix_f32 v122, v6, v22, v180 op_sel_hi:[0,1,0]
	v_fma_mix_f32 v122, v7, v22, v122 op_sel:[0,1,0] op_sel_hi:[0,1,0]
	v_add_f32_dpp v12, v12, v12 row_ror:1 row_mask:0xf bank_mask:0xf bound_ctrl:1
	v_fma_mix_f32 v122, v8, v23, v122 op_sel_hi:[0,1,0]
	v_fma_mix_f32 v122, v9, v23, v122 op_sel:[0,1,0] op_sel_hi:[0,1,0]
	v_add_f32_dpp v12, v12, v12 row_ror:2 row_mask:0xf bank_mask:0xf bound_ctrl:1
	v_pk_fma_f32 v[48:49], v[44:45], v[66:67], v[6:7] op_sel:[0,1,0]
	v_pk_fma_f32 v[50:51], v[46:47], v[66:67], v[8:9] op_sel:[0,1,0]
	v_add_f32_dpp v12, v12, v12 row_ror:4 row_mask:0xf bank_mask:0xf bound_ctrl:1
	v_add_f32_dpp v83, v83, v83 row_ror:8 row_mask:0xf bank_mask:0xc
	v_add_f32_dpp v83, v52, v52 row_ror:8 row_mask:0xf bank_mask:0x3
	v_add_f32_dpp v100, v100, v100 row_ror:8 row_mask:0xf bank_mask:0xc
	v_add_f32_dpp v12, v12, v12 row_ror:8 row_mask:0xf bank_mask:0xf bound_ctrl:1
	v_pk_fma_f32 v[6:7], v[40:41], v[12:13], v[48:49] op_sel_hi:[1,0,1] neg_lo:[1,0,0] neg_hi:[1,0,0]
	v_pk_fma_f32 v[8:9], v[42:43], v[12:13], v[50:51] op_sel_hi:[1,0,1] neg_lo:[1,0,0] neg_hi:[1,0,0]
	ds_read_b128 v[188:191], v10 offset:22784
	ds_read_b128 v[196:199], v10 offset:23296
	ds_read_b128 v[192:195], v10 offset:23040
	v_fma_mix_f32 v12, v6, v88, v180 op_sel_hi:[0,1,0]
	v_fma_mix_f32 v12, v7, v88, v12 op_sel:[0,1,0] op_sel_hi:[0,1,0]
	v_fma_mix_f32 v12, v8, v89, v12 op_sel_hi:[0,1,0]
	v_fma_mix_f32 v12, v9, v89, v12 op_sel:[0,1,0] op_sel_hi:[0,1,0]
	v_fma_mix_f32 v123, v6, v38, v180 op_sel_hi:[0,1,0]
	v_fma_mix_f32 v123, v7, v38, v123 op_sel:[0,1,0] op_sel_hi:[0,1,0]
	v_add_f32_dpp v12, v12, v12 row_ror:1 row_mask:0xf bank_mask:0xf bound_ctrl:1
	v_fma_mix_f32 v123, v8, v39, v123 op_sel_hi:[0,1,0]
	v_fma_mix_f32 v123, v9, v39, v123 op_sel:[0,1,0] op_sel_hi:[0,1,0]
	v_add_f32_dpp v12, v12, v12 row_ror:2 row_mask:0xf bank_mask:0xf bound_ctrl:1
	v_pk_fma_f32 v[48:49], v[96:97], v[68:69], v[6:7] op_sel_hi:[1,0,1]
	v_pk_fma_f32 v[50:51], v[98:99], v[68:69], v[8:9] op_sel_hi:[1,0,1]
	v_add_f32_dpp v12, v12, v12 row_ror:4 row_mask:0xf bank_mask:0xf bound_ctrl:1
	v_add_f32_dpp v100, v53, v53 row_ror:8 row_mask:0xf bank_mask:0x3
	v_add_f32_dpp v101, v101, v101 row_ror:8 row_mask:0xf bank_mask:0xc
	v_add_f32_dpp v101, v54, v54 row_ror:8 row_mask:0xf bank_mask:0x3
	v_add_f32_dpp v12, v12, v12 row_ror:8 row_mask:0xf bank_mask:0xf bound_ctrl:1
	v_pk_fma_f32 v[6:7], v[92:93], v[12:13], v[48:49] op_sel_hi:[1,0,1] neg_lo:[1,0,0] neg_hi:[1,0,0]
	v_pk_fma_f32 v[8:9], v[94:95], v[12:13], v[50:51] op_sel_hi:[1,0,1] neg_lo:[1,0,0] neg_hi:[1,0,0]
	ds_read_b128 v[204:207], v10 offset:23808
	ds_read_b128 v[200:203], v10 offset:23552
	ds_read_b128 v[212:215], v10 offset:24320
	ds_read_b128 v[208:211], v10 offset:24064
	v_fma_mix_f32 v12, v6, v110, v180 op_sel_hi:[0,1,0]
	v_fma_mix_f32 v12, v7, v110, v12 op_sel:[0,1,0] op_sel_hi:[0,1,0]
	v_fma_mix_f32 v12, v8, v111, v12 op_sel_hi:[0,1,0]
	v_fma_mix_f32 v12, v9, v111, v12 op_sel:[0,1,0] op_sel_hi:[0,1,0]
	v_fma_mix_f32 v124, v6, v90, v180 op_sel_hi:[0,1,0]
	v_fma_mix_f32 v124, v7, v90, v124 op_sel:[0,1,0] op_sel_hi:[0,1,0]
	v_add_f32_dpp v12, v12, v12 row_ror:1 row_mask:0xf bank_mask:0xf bound_ctrl:1
	v_fma_mix_f32 v124, v8, v91, v124 op_sel_hi:[0,1,0]
	v_fma_mix_f32 v124, v9, v91, v124 op_sel:[0,1,0] op_sel_hi:[0,1,0]
	v_add_f32_dpp v12, v12, v12 row_ror:2 row_mask:0xf bank_mask:0xf bound_ctrl:1
	v_pk_fma_f32 v[48:49], v[118:119], v[68:69], v[6:7] op_sel:[0,1,0]
	v_pk_fma_f32 v[50:51], v[120:121], v[68:69], v[8:9] op_sel:[0,1,0]
	v_add_f32_dpp v12, v12, v12 row_ror:4 row_mask:0xf bank_mask:0xf bound_ctrl:1
	v_add_f32_dpp v102, v102, v102 row_ror:8 row_mask:0xf bank_mask:0xc
	v_add_f32_dpp v102, v55, v55 row_ror:8 row_mask:0xf bank_mask:0x3
	v_add_f32_dpp v103, v103, v103 row_ror:8 row_mask:0xf bank_mask:0xc
	v_add_f32_dpp v12, v12, v12 row_ror:8 row_mask:0xf bank_mask:0xf bound_ctrl:1
	v_pk_fma_f32 v[6:7], v[114:115], v[12:13], v[48:49] op_sel_hi:[1,0,1] neg_lo:[1,0,0] neg_hi:[1,0,0]
	v_pk_fma_f32 v[8:9], v[116:117], v[12:13], v[50:51] op_sel_hi:[1,0,1] neg_lo:[1,0,0] neg_hi:[1,0,0]
	v_pk_mul_f32 v[6:7], v[6:7], v[106:107]
	v_pk_mul_f32 v[8:9], v[8:9], v[108:109]
	s_waitcnt lgkmcnt(0)
	s_nop 0
	ds_read_b128 v[20:23], v10 offset:24832
	ds_read_b128 v[28:31], v10 offset:25344
	ds_read_b128 v[24:27], v10 offset:25088
	v_fma_mix_f32 v12, v6, v142, v180 op_sel_hi:[0,1,0]
	v_fma_mix_f32 v12, v7, v142, v12 op_sel:[0,1,0] op_sel_hi:[0,1,0]
	v_fma_mix_f32 v12, v8, v143, v12 op_sel_hi:[0,1,0]
	v_fma_mix_f32 v12, v9, v143, v12 op_sel:[0,1,0] op_sel_hi:[0,1,0]
	v_fma_mix_f32 v125, v6, v112, v180 op_sel_hi:[0,1,0]
	v_fma_mix_f32 v125, v7, v112, v125 op_sel:[0,1,0] op_sel_hi:[0,1,0]
	v_add_f32_dpp v12, v12, v12 row_ror:1 row_mask:0xf bank_mask:0xf bound_ctrl:1
	v_fma_mix_f32 v125, v8, v113, v125 op_sel_hi:[0,1,0]
	v_fma_mix_f32 v125, v9, v113, v125 op_sel:[0,1,0] op_sel_hi:[0,1,0]
	v_add_f32_dpp v12, v12, v12 row_ror:2 row_mask:0xf bank_mask:0xf bound_ctrl:1
	v_pk_fma_f32 v[48:49], v[150:151], v[70:71], v[6:7] op_sel_hi:[1,0,1]
	v_pk_fma_f32 v[50:51], v[152:153], v[70:71], v[8:9] op_sel_hi:[1,0,1]
	v_add_f32_dpp v12, v12, v12 row_ror:4 row_mask:0xf bank_mask:0xf bound_ctrl:1
	v_add_f32_dpp v103, v56, v56 row_ror:8 row_mask:0xf bank_mask:0x3
	v_add_f32_dpp v104, v104, v104 row_ror:8 row_mask:0xf bank_mask:0xc
	v_add_f32_dpp v104, v57, v57 row_ror:8 row_mask:0xf bank_mask:0x3
	v_add_f32_dpp v12, v12, v12 row_ror:8 row_mask:0xf bank_mask:0xf bound_ctrl:1
	v_pk_fma_f32 v[6:7], v[146:147], v[12:13], v[48:49] op_sel_hi:[1,0,1] neg_lo:[1,0,0] neg_hi:[1,0,0]
	v_pk_fma_f32 v[8:9], v[148:149], v[12:13], v[50:51] op_sel_hi:[1,0,1] neg_lo:[1,0,0] neg_hi:[1,0,0]
	ds_read_b128 v[36:39], v10 offset:25856
	ds_read_b128 v[44:47], v10 offset:26368
	ds_read_b128 v[40:43], v10 offset:26112
	ds_read_b128 v[66:69], v11 offset:1536
	v_fma_mix_f32 v12, v6, v158, v180 op_sel_hi:[0,1,0]
	v_fma_mix_f32 v12, v7, v158, v12 op_sel:[0,1,0] op_sel_hi:[0,1,0]
	v_fma_mix_f32 v12, v8, v159, v12 op_sel_hi:[0,1,0]
	v_fma_mix_f32 v12, v9, v159, v12 op_sel:[0,1,0] op_sel_hi:[0,1,0]
	v_fma_mix_f32 v126, v6, v144, v180 op_sel_hi:[0,1,0]
	v_fma_mix_f32 v126, v7, v144, v126 op_sel:[0,1,0] op_sel_hi:[0,1,0]
	v_add_f32_dpp v12, v12, v12 row_ror:1 row_mask:0xf bank_mask:0xf bound_ctrl:1
	v_fma_mix_f32 v126, v8, v145, v126 op_sel_hi:[0,1,0]
	v_fma_mix_f32 v126, v9, v145, v126 op_sel:[0,1,0] op_sel_hi:[0,1,0]
	v_add_f32_dpp v12, v12, v12 row_ror:2 row_mask:0xf bank_mask:0xf bound_ctrl:1
	v_pk_fma_f32 v[48:49], v[166:167], v[70:71], v[6:7] op_sel:[0,1,0]
	v_pk_fma_f32 v[50:51], v[168:169], v[70:71], v[8:9] op_sel:[0,1,0]
	v_add_f32_dpp v12, v12, v12 row_ror:4 row_mask:0xf bank_mask:0xf bound_ctrl:1
	v_add_f32_dpp v105, v105, v105 row_ror:8 row_mask:0xf bank_mask:0xc
	v_add_f32_dpp v105, v81, v81 row_ror:8 row_mask:0xf bank_mask:0x3
	v_add_f32_dpp v12, v12, v12 row_ror:8 row_mask:0xf bank_mask:0xf bound_ctrl:1
	v_pk_fma_f32 v[6:7], v[162:163], v[12:13], v[48:49] op_sel_hi:[1,0,1] neg_lo:[1,0,0] neg_hi:[1,0,0]
	v_pk_fma_f32 v[8:9], v[164:165], v[12:13], v[50:51] op_sel_hi:[1,0,1] neg_lo:[1,0,0] neg_hi:[1,0,0]
	ds_read_b128 v[88:91], v10 offset:26880
	ds_read_b128 v[96:99], v10 offset:27392
	ds_read_b128 v[92:95], v10 offset:27136
	v_fma_mix_f32 v12, v6, v188, v180 op_sel_hi:[0,1,0]
	v_fma_mix_f32 v12, v7, v188, v12 op_sel:[0,1,0] op_sel_hi:[0,1,0]
	v_fma_mix_f32 v12, v8, v189, v12 op_sel_hi:[0,1,0]
	v_fma_mix_f32 v12, v9, v189, v12 op_sel:[0,1,0] op_sel_hi:[0,1,0]
	v_fma_mix_f32 v127, v6, v160, v180 op_sel_hi:[0,1,0]
	v_fma_mix_f32 v127, v7, v160, v127 op_sel:[0,1,0] op_sel_hi:[0,1,0]
	v_add_f32_dpp v12, v12, v12 row_ror:1 row_mask:0xf bank_mask:0xf bound_ctrl:1
	v_fma_mix_f32 v127, v8, v161, v127 op_sel_hi:[0,1,0]
	v_fma_mix_f32 v127, v9, v161, v127 op_sel:[0,1,0] op_sel_hi:[0,1,0]
	v_add_f32_dpp v12, v12, v12 row_ror:2 row_mask:0xf bank_mask:0xf bound_ctrl:1
	v_pk_fma_f32 v[48:49], v[196:197], v[72:73], v[6:7] op_sel_hi:[1,0,1]
	v_pk_fma_f32 v[50:51], v[198:199], v[72:73], v[8:9] op_sel_hi:[1,0,1]
	v_add_f32_dpp v12, v12, v12 row_ror:4 row_mask:0xf bank_mask:0xf bound_ctrl:1
	v_add_f32_dpp v61, v61, v61 row_ror:8 row_mask:0xf bank_mask:0xc
	v_add_f32_dpp v61, v82, v82 row_ror:8 row_mask:0xf bank_mask:0x3
	v_add_f32_dpp v12, v12, v12 row_ror:8 row_mask:0xf bank_mask:0xf bound_ctrl:1
	v_pk_fma_f32 v[6:7], v[192:193], v[12:13], v[48:49] op_sel_hi:[1,0,1] neg_lo:[1,0,0] neg_hi:[1,0,0]
	v_pk_fma_f32 v[8:9], v[194:195], v[12:13], v[50:51] op_sel_hi:[1,0,1] neg_lo:[1,0,0] neg_hi:[1,0,0]
	ds_read_b128 v[110:113], v10 offset:27904
	ds_read_b128 v[106:109], v10 offset:27648
	ds_read_b128 v[118:121], v10 offset:28416
	ds_read_b128 v[114:117], v10 offset:28160
	v_fma_mix_f32 v12, v6, v204, v180 op_sel_hi:[0,1,0]
	v_fma_mix_f32 v12, v7, v204, v12 op_sel:[0,1,0] op_sel_hi:[0,1,0]
	v_fma_mix_f32 v12, v8, v205, v12 op_sel_hi:[0,1,0]
	v_fma_mix_f32 v12, v9, v205, v12 op_sel:[0,1,0] op_sel_hi:[0,1,0]
	v_fma_mix_f32 v128, v6, v190, v180 op_sel_hi:[0,1,0]
	v_fma_mix_f32 v128, v7, v190, v128 op_sel:[0,1,0] op_sel_hi:[0,1,0]
	v_add_f32_dpp v12, v12, v12 row_ror:1 row_mask:0xf bank_mask:0xf bound_ctrl:1
	v_fma_mix_f32 v128, v8, v191, v128 op_sel_hi:[0,1,0]
	v_fma_mix_f32 v128, v9, v191, v128 op_sel:[0,1,0] op_sel_hi:[0,1,0]
	v_add_f32_dpp v12, v12, v12 row_ror:2 row_mask:0xf bank_mask:0xf bound_ctrl:1
	v_pk_fma_f32 v[48:49], v[212:213], v[72:73], v[6:7] op_sel:[0,1,0]
	v_pk_fma_f32 v[50:51], v[214:215], v[72:73], v[8:9] op_sel:[0,1,0]
	v_add_f32_dpp v12, v12, v12 row_ror:4 row_mask:0xf bank_mask:0xf bound_ctrl:1
	v_add_f32_dpp v103, v103, v103 row_ror:4 row_mask:0xf bank_mask:0xa
	v_add_f32_dpp v103, v83, v83 row_ror:12 row_mask:0xf bank_mask:0x5
	v_add_f32_dpp v104, v104, v104 row_ror:4 row_mask:0xf bank_mask:0xa
	v_add_f32_dpp v12, v12, v12 row_ror:8 row_mask:0xf bank_mask:0xf bound_ctrl:1
	v_pk_fma_f32 v[6:7], v[208:209], v[12:13], v[48:49] op_sel_hi:[1,0,1] neg_lo:[1,0,0] neg_hi:[1,0,0]
	v_pk_fma_f32 v[8:9], v[210:211], v[12:13], v[50:51] op_sel_hi:[1,0,1] neg_lo:[1,0,0] neg_hi:[1,0,0]
	v_pk_mul_f32 v[6:7], v[6:7], v[200:201]
	v_pk_mul_f32 v[8:9], v[8:9], v[202:203]
	s_waitcnt lgkmcnt(0)
	s_nop 0
	ds_read_b128 v[142:145], v10 offset:28928
	ds_read_b128 v[150:153], v10 offset:29440
	ds_read_b128 v[146:149], v10 offset:29184
	v_fma_mix_f32 v12, v6, v20, v180 op_sel_hi:[0,1,0]
	v_fma_mix_f32 v12, v7, v20, v12 op_sel:[0,1,0] op_sel_hi:[0,1,0]
	v_fma_mix_f32 v12, v8, v21, v12 op_sel_hi:[0,1,0]
	v_fma_mix_f32 v12, v9, v21, v12 op_sel:[0,1,0] op_sel_hi:[0,1,0]
	v_fma_mix_f32 v129, v6, v206, v180 op_sel_hi:[0,1,0]
	v_fma_mix_f32 v129, v7, v206, v129 op_sel:[0,1,0] op_sel_hi:[0,1,0]
	v_add_f32_dpp v12, v12, v12 row_ror:1 row_mask:0xf bank_mask:0xf bound_ctrl:1
	v_fma_mix_f32 v129, v8, v207, v129 op_sel_hi:[0,1,0]
	v_fma_mix_f32 v129, v9, v207, v129 op_sel:[0,1,0] op_sel_hi:[0,1,0]
	v_add_f32_dpp v12, v12, v12 row_ror:2 row_mask:0xf bank_mask:0xf bound_ctrl:1
	v_pk_fma_f32 v[48:49], v[28:29], v[66:67], v[6:7] op_sel_hi:[1,0,1]
	v_pk_fma_f32 v[50:51], v[30:31], v[66:67], v[8:9] op_sel_hi:[1,0,1]
	v_add_f32_dpp v12, v12, v12 row_ror:4 row_mask:0xf bank_mask:0xf bound_ctrl:1
	v_add_f32_dpp v104, v100, v100 row_ror:12 row_mask:0xf bank_mask:0x5
	v_add_f32_dpp v105, v105, v105 row_ror:4 row_mask:0xf bank_mask:0xa
	v_add_f32_dpp v105, v101, v101 row_ror:12 row_mask:0xf bank_mask:0x5
	v_add_f32_dpp v12, v12, v12 row_ror:8 row_mask:0xf bank_mask:0xf bound_ctrl:1
	v_pk_fma_f32 v[6:7], v[24:25], v[12:13], v[48:49] op_sel_hi:[1,0,1] neg_lo:[1,0,0] neg_hi:[1,0,0]
	v_pk_fma_f32 v[8:9], v[26:27], v[12:13], v[50:51] op_sel_hi:[1,0,1] neg_lo:[1,0,0] neg_hi:[1,0,0]
	ds_read_b128 v[158:161], v10 offset:29952
	ds_read_b128 v[166:169], v10 offset:30464
	ds_read_b128 v[162:165], v10 offset:30208
	ds_read_b128 v[70:73], v11 offset:1792
	v_fma_mix_f32 v12, v6, v36, v180 op_sel_hi:[0,1,0]
	v_fma_mix_f32 v12, v7, v36, v12 op_sel:[0,1,0] op_sel_hi:[0,1,0]
	v_fma_mix_f32 v12, v8, v37, v12 op_sel_hi:[0,1,0]
	v_fma_mix_f32 v12, v9, v37, v12 op_sel:[0,1,0] op_sel_hi:[0,1,0]
	v_fma_mix_f32 v130, v6, v22, v180 op_sel_hi:[0,1,0]
	v_fma_mix_f32 v130, v7, v22, v130 op_sel:[0,1,0] op_sel_hi:[0,1,0]
	v_add_f32_dpp v12, v12, v12 row_ror:1 row_mask:0xf bank_mask:0xf bound_ctrl:1
	v_fma_mix_f32 v130, v8, v23, v130 op_sel_hi:[0,1,0]
	v_fma_mix_f32 v130, v9, v23, v130 op_sel:[0,1,0] op_sel_hi:[0,1,0]
	v_add_f32_dpp v12, v12, v12 row_ror:2 row_mask:0xf bank_mask:0xf bound_ctrl:1
	v_pk_fma_f32 v[48:49], v[44:45], v[66:67], v[6:7] op_sel:[0,1,0]
	v_pk_fma_f32 v[50:51], v[46:47], v[66:67], v[8:9] op_sel:[0,1,0]
	v_add_f32_dpp v12, v12, v12 row_ror:4 row_mask:0xf bank_mask:0xf bound_ctrl:1
	v_add_f32_dpp v61, v61, v61 row_ror:4 row_mask:0xf bank_mask:0xa
	v_add_f32_dpp v61, v102, v102 row_ror:12 row_mask:0xf bank_mask:0x5
	v_add_f32_dpp v12, v12, v12 row_ror:8 row_mask:0xf bank_mask:0xf bound_ctrl:1
	v_pk_fma_f32 v[6:7], v[40:41], v[12:13], v[48:49] op_sel_hi:[1,0,1] neg_lo:[1,0,0] neg_hi:[1,0,0]
	v_pk_fma_f32 v[8:9], v[42:43], v[12:13], v[50:51] op_sel_hi:[1,0,1] neg_lo:[1,0,0] neg_hi:[1,0,0]
	ds_read_b128 v[188:191], v10 offset:30976
	ds_read_b128 v[196:199], v10 offset:31488
	ds_read_b128 v[192:195], v10 offset:31232
	v_fma_mix_f32 v12, v6, v88, v180 op_sel_hi:[0,1,0]
	v_fma_mix_f32 v12, v7, v88, v12 op_sel:[0,1,0] op_sel_hi:[0,1,0]
	v_fma_mix_f32 v12, v8, v89, v12 op_sel_hi:[0,1,0]
	v_fma_mix_f32 v12, v9, v89, v12 op_sel:[0,1,0] op_sel_hi:[0,1,0]
	v_fma_mix_f32 v131, v6, v38, v180 op_sel_hi:[0,1,0]
	v_fma_mix_f32 v131, v7, v38, v131 op_sel:[0,1,0] op_sel_hi:[0,1,0]
	v_add_f32_dpp v12, v12, v12 row_ror:1 row_mask:0xf bank_mask:0xf bound_ctrl:1
	v_fma_mix_f32 v131, v8, v39, v131 op_sel_hi:[0,1,0]
	v_fma_mix_f32 v131, v9, v39, v131 op_sel:[0,1,0] op_sel_hi:[0,1,0]
	v_add_f32_dpp v12, v12, v12 row_ror:2 row_mask:0xf bank_mask:0xf bound_ctrl:1
	v_pk_fma_f32 v[48:49], v[96:97], v[68:69], v[6:7] op_sel_hi:[1,0,1]
	v_pk_fma_f32 v[50:51], v[98:99], v[68:69], v[8:9] op_sel_hi:[1,0,1]
	v_add_f32_dpp v12, v12, v12 row_ror:4 row_mask:0xf bank_mask:0xf bound_ctrl:1
	v_cndmask_b32_e64 v62, v105, v103, s[38:39]
	v_cndmask_b32_e64 v63, v103, v105, s[38:39]
	v_add_f32_dpp v12, v12, v12 row_ror:8 row_mask:0xf bank_mask:0xf bound_ctrl:1
	v_pk_fma_f32 v[6:7], v[92:93], v[12:13], v[48:49] op_sel_hi:[1,0,1] neg_lo:[1,0,0] neg_hi:[1,0,0]
	v_pk_fma_f32 v[8:9], v[94:95], v[12:13], v[50:51] op_sel_hi:[1,0,1] neg_lo:[1,0,0] neg_hi:[1,0,0]
	ds_read_b128 v[204:207], v10 offset:32000
	ds_read_b128 v[200:203], v10 offset:31744
	ds_read_b128 v[212:215], v10 offset:32512
	ds_read_b128 v[208:211], v10 offset:32256
	v_fma_mix_f32 v12, v6, v110, v180 op_sel_hi:[0,1,0]
	v_fma_mix_f32 v12, v7, v110, v12 op_sel:[0,1,0] op_sel_hi:[0,1,0]
	v_fma_mix_f32 v12, v8, v111, v12 op_sel_hi:[0,1,0]
	v_fma_mix_f32 v12, v9, v111, v12 op_sel:[0,1,0] op_sel_hi:[0,1,0]
	v_fma_mix_f32 v132, v6, v90, v180 op_sel_hi:[0,1,0]
	v_fma_mix_f32 v132, v7, v90, v132 op_sel:[0,1,0] op_sel_hi:[0,1,0]
	v_add_f32_dpp v12, v12, v12 row_ror:1 row_mask:0xf bank_mask:0xf bound_ctrl:1
	v_fma_mix_f32 v132, v8, v91, v132 op_sel_hi:[0,1,0]
	v_fma_mix_f32 v132, v9, v91, v132 op_sel:[0,1,0] op_sel_hi:[0,1,0]
	v_add_f32_dpp v12, v12, v12 row_ror:2 row_mask:0xf bank_mask:0xf bound_ctrl:1
	v_pk_fma_f32 v[48:49], v[118:119], v[68:69], v[6:7] op_sel:[0,1,0]
	v_pk_fma_f32 v[50:51], v[120:121], v[68:69], v[8:9] op_sel:[0,1,0]
	v_add_f32_dpp v12, v12, v12 row_ror:4 row_mask:0xf bank_mask:0xf bound_ctrl:1
	v_cndmask_b32_e64 v64, v61, v104, s[38:39]
	v_cndmask_b32_e64 v65, v104, v61, s[38:39]
	v_add_f32_dpp v12, v12, v12 row_ror:8 row_mask:0xf bank_mask:0xf bound_ctrl:1
	v_pk_fma_f32 v[6:7], v[114:115], v[12:13], v[48:49] op_sel_hi:[1,0,1] neg_lo:[1,0,0] neg_hi:[1,0,0]
	v_pk_fma_f32 v[8:9], v[116:117], v[12:13], v[50:51] op_sel_hi:[1,0,1] neg_lo:[1,0,0] neg_hi:[1,0,0]
	v_pk_mul_f32 v[6:7], v[6:7], v[106:107]
	v_pk_mul_f32 v[8:9], v[8:9], v[108:109]
	s_waitcnt lgkmcnt(0)
	s_nop 0
	ds_read_b128 v[20:23], v10 offset:33024
	ds_read_b128 v[28:31], v10 offset:33536
	ds_read_b128 v[24:27], v10 offset:33280
	v_fma_mix_f32 v12, v6, v142, v180 op_sel_hi:[0,1,0]
	v_fma_mix_f32 v12, v7, v142, v12 op_sel:[0,1,0] op_sel_hi:[0,1,0]
	v_fma_mix_f32 v12, v8, v143, v12 op_sel_hi:[0,1,0]
	v_fma_mix_f32 v12, v9, v143, v12 op_sel:[0,1,0] op_sel_hi:[0,1,0]
	v_fma_mix_f32 v133, v6, v112, v180 op_sel_hi:[0,1,0]
	v_fma_mix_f32 v133, v7, v112, v133 op_sel:[0,1,0] op_sel_hi:[0,1,0]
	v_add_f32_dpp v12, v12, v12 row_ror:1 row_mask:0xf bank_mask:0xf bound_ctrl:1
	v_fma_mix_f32 v133, v8, v113, v133 op_sel_hi:[0,1,0]
	v_fma_mix_f32 v133, v9, v113, v133 op_sel:[0,1,0] op_sel_hi:[0,1,0]
	v_add_f32_dpp v12, v12, v12 row_ror:2 row_mask:0xf bank_mask:0xf bound_ctrl:1
	v_pk_fma_f32 v[48:49], v[150:151], v[70:71], v[6:7] op_sel_hi:[1,0,1]
	v_pk_fma_f32 v[50:51], v[152:153], v[70:71], v[8:9] op_sel_hi:[1,0,1]
	v_add_f32_dpp v12, v12, v12 row_ror:4 row_mask:0xf bank_mask:0xf bound_ctrl:1
	v_add_f32_dpp v62, v63, v62 quad_perm:[2,3,0,1] row_mask:0xf bank_mask:0xf bound_ctrl:1
	v_add_f32_dpp v63, v65, v64 quad_perm:[2,3,0,1] row_mask:0xf bank_mask:0xf bound_ctrl:1
	v_add_f32_dpp v12, v12, v12 row_ror:8 row_mask:0xf bank_mask:0xf bound_ctrl:1
	v_pk_fma_f32 v[6:7], v[146:147], v[12:13], v[48:49] op_sel_hi:[1,0,1] neg_lo:[1,0,0] neg_hi:[1,0,0]
	v_pk_fma_f32 v[8:9], v[148:149], v[12:13], v[50:51] op_sel_hi:[1,0,1] neg_lo:[1,0,0] neg_hi:[1,0,0]
	ds_read_b128 v[36:39], v10 offset:34048
	ds_read_b128 v[44:47], v10 offset:34560
	ds_read_b128 v[40:43], v10 offset:34304
	ds_read_b128 v[66:69], v11 offset:2048
	v_fma_mix_f32 v12, v6, v158, v180 op_sel_hi:[0,1,0]
	v_fma_mix_f32 v12, v7, v158, v12 op_sel:[0,1,0] op_sel_hi:[0,1,0]
	v_fma_mix_f32 v12, v8, v159, v12 op_sel_hi:[0,1,0]
	v_fma_mix_f32 v12, v9, v159, v12 op_sel:[0,1,0] op_sel_hi:[0,1,0]
	v_fma_mix_f32 v134, v6, v144, v180 op_sel_hi:[0,1,0]
	v_fma_mix_f32 v134, v7, v144, v134 op_sel:[0,1,0] op_sel_hi:[0,1,0]
	v_add_f32_dpp v12, v12, v12 row_ror:1 row_mask:0xf bank_mask:0xf bound_ctrl:1
	v_fma_mix_f32 v134, v8, v145, v134 op_sel_hi:[0,1,0]
	v_fma_mix_f32 v134, v9, v145, v134 op_sel:[0,1,0] op_sel_hi:[0,1,0]
	v_add_f32_dpp v12, v12, v12 row_ror:2 row_mask:0xf bank_mask:0xf bound_ctrl:1
	v_pk_fma_f32 v[48:49], v[166:167], v[70:71], v[6:7] op_sel:[0,1,0]
	v_pk_fma_f32 v[50:51], v[168:169], v[70:71], v[8:9] op_sel:[0,1,0]
	v_add_f32_dpp v12, v12, v12 row_ror:4 row_mask:0xf bank_mask:0xf bound_ctrl:1
	v_cndmask_b32_e64 v65, v63, v62, s[40:41]
	v_cndmask_b32_e64 v62, v62, v63, s[40:41]
	v_add_f32_dpp v12, v12, v12 row_ror:8 row_mask:0xf bank_mask:0xf bound_ctrl:1
	v_pk_fma_f32 v[6:7], v[162:163], v[12:13], v[48:49] op_sel_hi:[1,0,1] neg_lo:[1,0,0] neg_hi:[1,0,0]
	v_pk_fma_f32 v[8:9], v[164:165], v[12:13], v[50:51] op_sel_hi:[1,0,1] neg_lo:[1,0,0] neg_hi:[1,0,0]
	ds_read_b128 v[88:91], v10 offset:35072
	ds_read_b128 v[96:99], v10 offset:35584
	ds_read_b128 v[92:95], v10 offset:35328
	v_fma_mix_f32 v12, v6, v188, v180 op_sel_hi:[0,1,0]
	v_fma_mix_f32 v12, v7, v188, v12 op_sel:[0,1,0] op_sel_hi:[0,1,0]
	v_fma_mix_f32 v12, v8, v189, v12 op_sel_hi:[0,1,0]
	v_fma_mix_f32 v12, v9, v189, v12 op_sel:[0,1,0] op_sel_hi:[0,1,0]
	v_fma_mix_f32 v135, v6, v160, v180 op_sel_hi:[0,1,0]
	v_fma_mix_f32 v135, v7, v160, v135 op_sel:[0,1,0] op_sel_hi:[0,1,0]
	v_add_f32_dpp v12, v12, v12 row_ror:1 row_mask:0xf bank_mask:0xf bound_ctrl:1
	v_fma_mix_f32 v135, v8, v161, v135 op_sel_hi:[0,1,0]
	v_fma_mix_f32 v135, v9, v161, v135 op_sel:[0,1,0] op_sel_hi:[0,1,0]
	v_add_f32_dpp v12, v12, v12 row_ror:2 row_mask:0xf bank_mask:0xf bound_ctrl:1
	v_pk_fma_f32 v[48:49], v[196:197], v[72:73], v[6:7] op_sel_hi:[1,0,1]
	v_pk_fma_f32 v[50:51], v[198:199], v[72:73], v[8:9] op_sel_hi:[1,0,1]
	v_add_f32_dpp v12, v12, v12 row_ror:4 row_mask:0xf bank_mask:0xf bound_ctrl:1
	v_add_f32_dpp v62, v62, v65 quad_perm:[1,0,3,2] row_mask:0xf bank_mask:0xf bound_ctrl:1
	v_cvt_pk_bf16_f32 v62, v62, v62
	v_add_f32_dpp v12, v12, v12 row_ror:8 row_mask:0xf bank_mask:0xf bound_ctrl:1
	v_pk_fma_f32 v[6:7], v[192:193], v[12:13], v[48:49] op_sel_hi:[1,0,1] neg_lo:[1,0,0] neg_hi:[1,0,0]
	v_pk_fma_f32 v[8:9], v[194:195], v[12:13], v[50:51] op_sel_hi:[1,0,1] neg_lo:[1,0,0] neg_hi:[1,0,0]
	ds_read_b128 v[110:113], v10 offset:36096
	ds_read_b128 v[106:109], v10 offset:35840
	ds_read_b128 v[118:121], v10 offset:36608
	ds_read_b128 v[114:117], v10 offset:36352
	v_fma_mix_f32 v12, v6, v204, v180 op_sel_hi:[0,1,0]
	v_fma_mix_f32 v12, v7, v204, v12 op_sel:[0,1,0] op_sel_hi:[0,1,0]
	v_fma_mix_f32 v12, v8, v205, v12 op_sel_hi:[0,1,0]
	v_fma_mix_f32 v12, v9, v205, v12 op_sel:[0,1,0] op_sel_hi:[0,1,0]
	v_fma_mix_f32 v136, v6, v190, v180 op_sel_hi:[0,1,0]
	v_fma_mix_f32 v136, v7, v190, v136 op_sel:[0,1,0] op_sel_hi:[0,1,0]
	v_add_f32_dpp v12, v12, v12 row_ror:1 row_mask:0xf bank_mask:0xf bound_ctrl:1
	v_fma_mix_f32 v136, v8, v191, v136 op_sel_hi:[0,1,0]
	v_fma_mix_f32 v136, v9, v191, v136 op_sel:[0,1,0] op_sel_hi:[0,1,0]
	v_add_f32_dpp v12, v12, v12 row_ror:2 row_mask:0xf bank_mask:0xf bound_ctrl:1
	v_pk_fma_f32 v[48:49], v[212:213], v[72:73], v[6:7] op_sel:[0,1,0]
	v_pk_fma_f32 v[50:51], v[214:215], v[72:73], v[8:9] op_sel:[0,1,0]
	v_add_f32_dpp v12, v12, v12 row_ror:4 row_mask:0xf bank_mask:0xf bound_ctrl:1
	global_store_short v[2:3], v62, off
	v_lshl_add_u64 v[2:3], v[2:3], 0, s[84:85]
	v_add_f32_dpp v12, v12, v12 row_ror:8 row_mask:0xf bank_mask:0xf bound_ctrl:1
	v_pk_fma_f32 v[6:7], v[208:209], v[12:13], v[48:49] op_sel_hi:[1,0,1] neg_lo:[1,0,0] neg_hi:[1,0,0]
	v_pk_fma_f32 v[8:9], v[210:211], v[12:13], v[50:51] op_sel_hi:[1,0,1] neg_lo:[1,0,0] neg_hi:[1,0,0]
	v_pk_mul_f32 v[6:7], v[6:7], v[200:201]
	v_pk_mul_f32 v[8:9], v[8:9], v[202:203]
	s_waitcnt lgkmcnt(0)
	s_nop 0
	ds_read_b128 v[142:145], v10 offset:37120
	ds_read_b128 v[150:153], v10 offset:37632
	ds_read_b128 v[146:149], v10 offset:37376
	v_fma_mix_f32 v12, v6, v20, v180 op_sel_hi:[0,1,0]
	v_fma_mix_f32 v12, v7, v20, v12 op_sel:[0,1,0] op_sel_hi:[0,1,0]
	v_fma_mix_f32 v12, v8, v21, v12 op_sel_hi:[0,1,0]
	v_fma_mix_f32 v12, v9, v21, v12 op_sel:[0,1,0] op_sel_hi:[0,1,0]
	v_fma_mix_f32 v137, v6, v206, v180 op_sel_hi:[0,1,0]
	v_fma_mix_f32 v137, v7, v206, v137 op_sel:[0,1,0] op_sel_hi:[0,1,0]
	v_add_f32_dpp v12, v12, v12 row_ror:1 row_mask:0xf bank_mask:0xf bound_ctrl:1
	v_fma_mix_f32 v137, v8, v207, v137 op_sel_hi:[0,1,0]
	v_fma_mix_f32 v137, v9, v207, v137 op_sel:[0,1,0] op_sel_hi:[0,1,0]
	v_add_f32_dpp v12, v12, v12 row_ror:2 row_mask:0xf bank_mask:0xf bound_ctrl:1
	v_pk_fma_f32 v[48:49], v[28:29], v[66:67], v[6:7] op_sel_hi:[1,0,1]
	v_pk_fma_f32 v[50:51], v[30:31], v[66:67], v[8:9] op_sel_hi:[1,0,1]
	v_add_f32_dpp v12, v12, v12 row_ror:4 row_mask:0xf bank_mask:0xf bound_ctrl:1
	s_nop 1
	s_nop 0
	v_add_f32_dpp v12, v12, v12 row_ror:8 row_mask:0xf bank_mask:0xf bound_ctrl:1
	v_pk_fma_f32 v[6:7], v[24:25], v[12:13], v[48:49] op_sel_hi:[1,0,1] neg_lo:[1,0,0] neg_hi:[1,0,0]
	v_pk_fma_f32 v[8:9], v[26:27], v[12:13], v[50:51] op_sel_hi:[1,0,1] neg_lo:[1,0,0] neg_hi:[1,0,0]
	ds_read_b128 v[158:161], v10 offset:38144
	ds_read_b128 v[166:169], v10 offset:38656
	ds_read_b128 v[162:165], v10 offset:38400
	ds_read_b128 v[70:73], v11 offset:2304
	v_fma_mix_f32 v12, v6, v36, v180 op_sel_hi:[0,1,0]
	v_fma_mix_f32 v12, v7, v36, v12 op_sel:[0,1,0] op_sel_hi:[0,1,0]
	v_fma_mix_f32 v12, v8, v37, v12 op_sel_hi:[0,1,0]
	v_fma_mix_f32 v12, v9, v37, v12 op_sel:[0,1,0] op_sel_hi:[0,1,0]
	v_fma_mix_f32 v52, v6, v22, v180 op_sel_hi:[0,1,0]
	v_fma_mix_f32 v52, v7, v22, v52 op_sel:[0,1,0] op_sel_hi:[0,1,0]
	v_add_f32_dpp v12, v12, v12 row_ror:1 row_mask:0xf bank_mask:0xf bound_ctrl:1
	v_fma_mix_f32 v52, v8, v23, v52 op_sel_hi:[0,1,0]
	v_fma_mix_f32 v52, v9, v23, v52 op_sel:[0,1,0] op_sel_hi:[0,1,0]
	v_add_f32_dpp v12, v12, v12 row_ror:2 row_mask:0xf bank_mask:0xf bound_ctrl:1
	v_pk_fma_f32 v[48:49], v[44:45], v[66:67], v[6:7] op_sel:[0,1,0]
	v_pk_fma_f32 v[50:51], v[46:47], v[66:67], v[8:9] op_sel:[0,1,0]
	v_add_f32_dpp v12, v12, v12 row_ror:4 row_mask:0xf bank_mask:0xf bound_ctrl:1
	v_add_f32_dpp v130, v130, v130 row_ror:8 row_mask:0xf bank_mask:0xc
	v_add_f32_dpp v130, v122, v122 row_ror:8 row_mask:0xf bank_mask:0x3
	v_add_f32_dpp v131, v131, v131 row_ror:8 row_mask:0xf bank_mask:0xc
	v_add_f32_dpp v12, v12, v12 row_ror:8 row_mask:0xf bank_mask:0xf bound_ctrl:1
	v_pk_fma_f32 v[6:7], v[40:41], v[12:13], v[48:49] op_sel_hi:[1,0,1] neg_lo:[1,0,0] neg_hi:[1,0,0]
	v_pk_fma_f32 v[8:9], v[42:43], v[12:13], v[50:51] op_sel_hi:[1,0,1] neg_lo:[1,0,0] neg_hi:[1,0,0]
	ds_read_b128 v[188:191], v10 offset:39168
	ds_read_b128 v[196:199], v10 offset:39680
	ds_read_b128 v[192:195], v10 offset:39424
	v_fma_mix_f32 v12, v6, v88, v180 op_sel_hi:[0,1,0]
	v_fma_mix_f32 v12, v7, v88, v12 op_sel:[0,1,0] op_sel_hi:[0,1,0]
	v_fma_mix_f32 v12, v8, v89, v12 op_sel_hi:[0,1,0]
	v_fma_mix_f32 v12, v9, v89, v12 op_sel:[0,1,0] op_sel_hi:[0,1,0]
	v_fma_mix_f32 v53, v6, v38, v180 op_sel_hi:[0,1,0]
	v_fma_mix_f32 v53, v7, v38, v53 op_sel:[0,1,0] op_sel_hi:[0,1,0]
	v_add_f32_dpp v12, v12, v12 row_ror:1 row_mask:0xf bank_mask:0xf bound_ctrl:1
	v_fma_mix_f32 v53, v8, v39, v53 op_sel_hi:[0,1,0]
	v_fma_mix_f32 v53, v9, v39, v53 op_sel:[0,1,0] op_sel_hi:[0,1,0]
	v_add_f32_dpp v12, v12, v12 row_ror:2 row_mask:0xf bank_mask:0xf bound_ctrl:1
	v_pk_fma_f32 v[48:49], v[96:97], v[68:69], v[6:7] op_sel_hi:[1,0,1]
	v_pk_fma_f32 v[50:51], v[98:99], v[68:69], v[8:9] op_sel_hi:[1,0,1]
	v_add_f32_dpp v12, v12, v12 row_ror:4 row_mask:0xf bank_mask:0xf bound_ctrl:1
	v_add_f32_dpp v131, v123, v123 row_ror:8 row_mask:0xf bank_mask:0x3
	v_add_f32_dpp v132, v132, v132 row_ror:8 row_mask:0xf bank_mask:0xc
	v_add_f32_dpp v132, v124, v124 row_ror:8 row_mask:0xf bank_mask:0x3
	v_add_f32_dpp v12, v12, v12 row_ror:8 row_mask:0xf bank_mask:0xf bound_ctrl:1
	v_pk_fma_f32 v[6:7], v[92:93], v[12:13], v[48:49] op_sel_hi:[1,0,1] neg_lo:[1,0,0] neg_hi:[1,0,0]
	v_pk_fma_f32 v[8:9], v[94:95], v[12:13], v[50:51] op_sel_hi:[1,0,1] neg_lo:[1,0,0] neg_hi:[1,0,0]
	ds_read_b128 v[204:207], v10 offset:40192
	ds_read_b128 v[200:203], v10 offset:39936
	ds_read_b128 v[212:215], v10 offset:40704
	ds_read_b128 v[208:211], v10 offset:40448
	v_fma_mix_f32 v12, v6, v110, v180 op_sel_hi:[0,1,0]
	v_fma_mix_f32 v12, v7, v110, v12 op_sel:[0,1,0] op_sel_hi:[0,1,0]
	v_fma_mix_f32 v12, v8, v111, v12 op_sel_hi:[0,1,0]
	v_fma_mix_f32 v12, v9, v111, v12 op_sel:[0,1,0] op_sel_hi:[0,1,0]
	v_fma_mix_f32 v54, v6, v90, v180 op_sel_hi:[0,1,0]
	v_fma_mix_f32 v54, v7, v90, v54 op_sel:[0,1,0] op_sel_hi:[0,1,0]
	v_add_f32_dpp v12, v12, v12 row_ror:1 row_mask:0xf bank_mask:0xf bound_ctrl:1
	v_fma_mix_f32 v54, v8, v91, v54 op_sel_hi:[0,1,0]
	v_fma_mix_f32 v54, v9, v91, v54 op_sel:[0,1,0] op_sel_hi:[0,1,0]
	v_add_f32_dpp v12, v12, v12 row_ror:2 row_mask:0xf bank_mask:0xf bound_ctrl:1
	v_pk_fma_f32 v[48:49], v[118:119], v[68:69], v[6:7] op_sel:[0,1,0]
	v_pk_fma_f32 v[50:51], v[120:121], v[68:69], v[8:9] op_sel:[0,1,0]
	v_add_f32_dpp v12, v12, v12 row_ror:4 row_mask:0xf bank_mask:0xf bound_ctrl:1
	v_add_f32_dpp v133, v133, v133 row_ror:8 row_mask:0xf bank_mask:0xc
	v_add_f32_dpp v133, v125, v125 row_ror:8 row_mask:0xf bank_mask:0x3
	v_add_f32_dpp v134, v134, v134 row_ror:8 row_mask:0xf bank_mask:0xc
	v_add_f32_dpp v12, v12, v12 row_ror:8 row_mask:0xf bank_mask:0xf bound_ctrl:1
	v_pk_fma_f32 v[6:7], v[114:115], v[12:13], v[48:49] op_sel_hi:[1,0,1] neg_lo:[1,0,0] neg_hi:[1,0,0]
	v_pk_fma_f32 v[8:9], v[116:117], v[12:13], v[50:51] op_sel_hi:[1,0,1] neg_lo:[1,0,0] neg_hi:[1,0,0]
	v_pk_mul_f32 v[6:7], v[6:7], v[106:107]
	v_pk_mul_f32 v[8:9], v[8:9], v[108:109]
	s_waitcnt lgkmcnt(0)
	s_nop 0
	ds_read_b128 v[20:23], v10 offset:41216
	ds_read_b128 v[28:31], v10 offset:41728
	ds_read_b128 v[24:27], v10 offset:41472
	v_fma_mix_f32 v12, v6, v142, v180 op_sel_hi:[0,1,0]
	v_fma_mix_f32 v12, v7, v142, v12 op_sel:[0,1,0] op_sel_hi:[0,1,0]
	v_fma_mix_f32 v12, v8, v143, v12 op_sel_hi:[0,1,0]
	v_fma_mix_f32 v12, v9, v143, v12 op_sel:[0,1,0] op_sel_hi:[0,1,0]
	v_fma_mix_f32 v55, v6, v112, v180 op_sel_hi:[0,1,0]
	v_fma_mix_f32 v55, v7, v112, v55 op_sel:[0,1,0] op_sel_hi:[0,1,0]
	v_add_f32_dpp v12, v12, v12 row_ror:1 row_mask:0xf bank_mask:0xf bound_ctrl:1
	v_fma_mix_f32 v55, v8, v113, v55 op_sel_hi:[0,1,0]
	v_fma_mix_f32 v55, v9, v113, v55 op_sel:[0,1,0] op_sel_hi:[0,1,0]
	v_add_f32_dpp v12, v12, v12 row_ror:2 row_mask:0xf bank_mask:0xf bound_ctrl:1
	v_pk_fma_f32 v[48:49], v[150:151], v[70:71], v[6:7] op_sel_hi:[1,0,1]
	v_pk_fma_f32 v[50:51], v[152:153], v[70:71], v[8:9] op_sel_hi:[1,0,1]
	v_add_f32_dpp v12, v12, v12 row_ror:4 row_mask:0xf bank_mask:0xf bound_ctrl:1
	v_add_f32_dpp v134, v126, v126 row_ror:8 row_mask:0xf bank_mask:0x3
	v_add_f32_dpp v135, v135, v135 row_ror:8 row_mask:0xf bank_mask:0xc
	v_add_f32_dpp v135, v127, v127 row_ror:8 row_mask:0xf bank_mask:0x3
	v_add_f32_dpp v12, v12, v12 row_ror:8 row_mask:0xf bank_mask:0xf bound_ctrl:1
	v_pk_fma_f32 v[6:7], v[146:147], v[12:13], v[48:49] op_sel_hi:[1,0,1] neg_lo:[1,0,0] neg_hi:[1,0,0]
	v_pk_fma_f32 v[8:9], v[148:149], v[12:13], v[50:51] op_sel_hi:[1,0,1] neg_lo:[1,0,0] neg_hi:[1,0,0]
	ds_read_b128 v[36:39], v10 offset:42240
	ds_read_b128 v[44:47], v10 offset:42752
	ds_read_b128 v[40:43], v10 offset:42496
	ds_read_b128 v[66:69], v11 offset:2560
	v_fma_mix_f32 v12, v6, v158, v180 op_sel_hi:[0,1,0]
	v_fma_mix_f32 v12, v7, v158, v12 op_sel:[0,1,0] op_sel_hi:[0,1,0]
	v_fma_mix_f32 v12, v8, v159, v12 op_sel_hi:[0,1,0]
	v_fma_mix_f32 v12, v9, v159, v12 op_sel:[0,1,0] op_sel_hi:[0,1,0]
	v_fma_mix_f32 v56, v6, v144, v180 op_sel_hi:[0,1,0]
	v_fma_mix_f32 v56, v7, v144, v56 op_sel:[0,1,0] op_sel_hi:[0,1,0]
	v_add_f32_dpp v12, v12, v12 row_ror:1 row_mask:0xf bank_mask:0xf bound_ctrl:1
	v_fma_mix_f32 v56, v8, v145, v56 op_sel_hi:[0,1,0]
	v_fma_mix_f32 v56, v9, v145, v56 op_sel:[0,1,0] op_sel_hi:[0,1,0]
	v_add_f32_dpp v12, v12, v12 row_ror:2 row_mask:0xf bank_mask:0xf bound_ctrl:1
	v_pk_fma_f32 v[48:49], v[166:167], v[70:71], v[6:7] op_sel:[0,1,0]
	v_pk_fma_f32 v[50:51], v[168:169], v[70:71], v[8:9] op_sel:[0,1,0]
	v_add_f32_dpp v12, v12, v12 row_ror:4 row_mask:0xf bank_mask:0xf bound_ctrl:1
	v_add_f32_dpp v136, v136, v136 row_ror:8 row_mask:0xf bank_mask:0xc
	v_add_f32_dpp v136, v128, v128 row_ror:8 row_mask:0xf bank_mask:0x3
	v_add_f32_dpp v12, v12, v12 row_ror:8 row_mask:0xf bank_mask:0xf bound_ctrl:1
	v_pk_fma_f32 v[6:7], v[162:163], v[12:13], v[48:49] op_sel_hi:[1,0,1] neg_lo:[1,0,0] neg_hi:[1,0,0]
	v_pk_fma_f32 v[8:9], v[164:165], v[12:13], v[50:51] op_sel_hi:[1,0,1] neg_lo:[1,0,0] neg_hi:[1,0,0]
	ds_read_b128 v[88:91], v10 offset:43264
	ds_read_b128 v[96:99], v10 offset:43776
	ds_read_b128 v[92:95], v10 offset:43520
	v_fma_mix_f32 v12, v6, v188, v180 op_sel_hi:[0,1,0]
	v_fma_mix_f32 v12, v7, v188, v12 op_sel:[0,1,0] op_sel_hi:[0,1,0]
	v_fma_mix_f32 v12, v8, v189, v12 op_sel_hi:[0,1,0]
	v_fma_mix_f32 v12, v9, v189, v12 op_sel:[0,1,0] op_sel_hi:[0,1,0]
	v_fma_mix_f32 v57, v6, v160, v180 op_sel_hi:[0,1,0]
	v_fma_mix_f32 v57, v7, v160, v57 op_sel:[0,1,0] op_sel_hi:[0,1,0]
	v_add_f32_dpp v12, v12, v12 row_ror:1 row_mask:0xf bank_mask:0xf bound_ctrl:1
	v_fma_mix_f32 v57, v8, v161, v57 op_sel_hi:[0,1,0]
	v_fma_mix_f32 v57, v9, v161, v57 op_sel:[0,1,0] op_sel_hi:[0,1,0]
	v_add_f32_dpp v12, v12, v12 row_ror:2 row_mask:0xf bank_mask:0xf bound_ctrl:1
	v_pk_fma_f32 v[48:49], v[196:197], v[72:73], v[6:7] op_sel_hi:[1,0,1]
	v_pk_fma_f32 v[50:51], v[198:199], v[72:73], v[8:9] op_sel_hi:[1,0,1]
	v_add_f32_dpp v12, v12, v12 row_ror:4 row_mask:0xf bank_mask:0xf bound_ctrl:1
	v_add_f32_dpp v137, v137, v137 row_ror:8 row_mask:0xf bank_mask:0xc
	v_add_f32_dpp v137, v129, v129 row_ror:8 row_mask:0xf bank_mask:0x3
	v_add_f32_dpp v12, v12, v12 row_ror:8 row_mask:0xf bank_mask:0xf bound_ctrl:1
	v_pk_fma_f32 v[6:7], v[192:193], v[12:13], v[48:49] op_sel_hi:[1,0,1] neg_lo:[1,0,0] neg_hi:[1,0,0]
	v_pk_fma_f32 v[8:9], v[194:195], v[12:13], v[50:51] op_sel_hi:[1,0,1] neg_lo:[1,0,0] neg_hi:[1,0,0]
	ds_read_b128 v[110:113], v10 offset:44288
	ds_read_b128 v[106:109], v10 offset:44032
	ds_read_b128 v[118:121], v10 offset:44800
	ds_read_b128 v[114:117], v10 offset:44544
	v_fma_mix_f32 v12, v6, v204, v180 op_sel_hi:[0,1,0]
	v_fma_mix_f32 v12, v7, v204, v12 op_sel:[0,1,0] op_sel_hi:[0,1,0]
	v_fma_mix_f32 v12, v8, v205, v12 op_sel_hi:[0,1,0]
	v_fma_mix_f32 v12, v9, v205, v12 op_sel:[0,1,0] op_sel_hi:[0,1,0]
	v_fma_mix_f32 v81, v6, v190, v180 op_sel_hi:[0,1,0]
	v_fma_mix_f32 v81, v7, v190, v81 op_sel:[0,1,0] op_sel_hi:[0,1,0]
	v_add_f32_dpp v12, v12, v12 row_ror:1 row_mask:0xf bank_mask:0xf bound_ctrl:1
	v_fma_mix_f32 v81, v8, v191, v81 op_sel_hi:[0,1,0]
	v_fma_mix_f32 v81, v9, v191, v81 op_sel:[0,1,0] op_sel_hi:[0,1,0]
	v_add_f32_dpp v12, v12, v12 row_ror:2 row_mask:0xf bank_mask:0xf bound_ctrl:1
	v_pk_fma_f32 v[48:49], v[212:213], v[72:73], v[6:7] op_sel:[0,1,0]
	v_pk_fma_f32 v[50:51], v[214:215], v[72:73], v[8:9] op_sel:[0,1,0]
	v_add_f32_dpp v12, v12, v12 row_ror:4 row_mask:0xf bank_mask:0xf bound_ctrl:1
	v_add_f32_dpp v134, v134, v134 row_ror:4 row_mask:0xf bank_mask:0xa
	v_add_f32_dpp v134, v130, v130 row_ror:12 row_mask:0xf bank_mask:0x5
	v_add_f32_dpp v135, v135, v135 row_ror:4 row_mask:0xf bank_mask:0xa
	v_add_f32_dpp v12, v12, v12 row_ror:8 row_mask:0xf bank_mask:0xf bound_ctrl:1
	v_pk_fma_f32 v[6:7], v[208:209], v[12:13], v[48:49] op_sel_hi:[1,0,1] neg_lo:[1,0,0] neg_hi:[1,0,0]
	v_pk_fma_f32 v[8:9], v[210:211], v[12:13], v[50:51] op_sel_hi:[1,0,1] neg_lo:[1,0,0] neg_hi:[1,0,0]
	v_pk_mul_f32 v[6:7], v[6:7], v[200:201]
	v_pk_mul_f32 v[8:9], v[8:9], v[202:203]
	s_waitcnt lgkmcnt(0)
	s_nop 0
	ds_read_b128 v[142:145], v10 offset:45312
	ds_read_b128 v[150:153], v10 offset:45824
	ds_read_b128 v[146:149], v10 offset:45568
	v_fma_mix_f32 v12, v6, v20, v180 op_sel_hi:[0,1,0]
	v_fma_mix_f32 v12, v7, v20, v12 op_sel:[0,1,0] op_sel_hi:[0,1,0]
	v_fma_mix_f32 v12, v8, v21, v12 op_sel_hi:[0,1,0]
	v_fma_mix_f32 v12, v9, v21, v12 op_sel:[0,1,0] op_sel_hi:[0,1,0]
	v_fma_mix_f32 v82, v6, v206, v180 op_sel_hi:[0,1,0]
	v_fma_mix_f32 v82, v7, v206, v82 op_sel:[0,1,0] op_sel_hi:[0,1,0]
	v_add_f32_dpp v12, v12, v12 row_ror:1 row_mask:0xf bank_mask:0xf bound_ctrl:1
	v_fma_mix_f32 v82, v8, v207, v82 op_sel_hi:[0,1,0]
	v_fma_mix_f32 v82, v9, v207, v82 op_sel:[0,1,0] op_sel_hi:[0,1,0]
	v_add_f32_dpp v12, v12, v12 row_ror:2 row_mask:0xf bank_mask:0xf bound_ctrl:1
	v_pk_fma_f32 v[48:49], v[28:29], v[66:67], v[6:7] op_sel_hi:[1,0,1]
	v_pk_fma_f32 v[50:51], v[30:31], v[66:67], v[8:9] op_sel_hi:[1,0,1]
	v_add_f32_dpp v12, v12, v12 row_ror:4 row_mask:0xf bank_mask:0xf bound_ctrl:1
	v_add_f32_dpp v135, v131, v131 row_ror:12 row_mask:0xf bank_mask:0x5
	v_add_f32_dpp v136, v136, v136 row_ror:4 row_mask:0xf bank_mask:0xa
	v_add_f32_dpp v136, v132, v132 row_ror:12 row_mask:0xf bank_mask:0x5
	v_add_f32_dpp v12, v12, v12 row_ror:8 row_mask:0xf bank_mask:0xf bound_ctrl:1
	v_pk_fma_f32 v[6:7], v[24:25], v[12:13], v[48:49] op_sel_hi:[1,0,1] neg_lo:[1,0,0] neg_hi:[1,0,0]
	v_pk_fma_f32 v[8:9], v[26:27], v[12:13], v[50:51] op_sel_hi:[1,0,1] neg_lo:[1,0,0] neg_hi:[1,0,0]
	ds_read_b128 v[158:161], v10 offset:46336
	ds_read_b128 v[166:169], v10 offset:46848
	ds_read_b128 v[162:165], v10 offset:46592
	ds_read_b128 v[70:73], v11 offset:2816
	v_fma_mix_f32 v12, v6, v36, v180 op_sel_hi:[0,1,0]
	v_fma_mix_f32 v12, v7, v36, v12 op_sel:[0,1,0] op_sel_hi:[0,1,0]
	v_fma_mix_f32 v12, v8, v37, v12 op_sel_hi:[0,1,0]
	v_fma_mix_f32 v12, v9, v37, v12 op_sel:[0,1,0] op_sel_hi:[0,1,0]
	v_fma_mix_f32 v83, v6, v22, v180 op_sel_hi:[0,1,0]
	v_fma_mix_f32 v83, v7, v22, v83 op_sel:[0,1,0] op_sel_hi:[0,1,0]
	v_add_f32_dpp v12, v12, v12 row_ror:1 row_mask:0xf bank_mask:0xf bound_ctrl:1
	v_fma_mix_f32 v83, v8, v23, v83 op_sel_hi:[0,1,0]
	v_fma_mix_f32 v83, v9, v23, v83 op_sel:[0,1,0] op_sel_hi:[0,1,0]
	v_add_f32_dpp v12, v12, v12 row_ror:2 row_mask:0xf bank_mask:0xf bound_ctrl:1
	v_pk_fma_f32 v[48:49], v[44:45], v[66:67], v[6:7] op_sel:[0,1,0]
	v_pk_fma_f32 v[50:51], v[46:47], v[66:67], v[8:9] op_sel:[0,1,0]
	v_add_f32_dpp v12, v12, v12 row_ror:4 row_mask:0xf bank_mask:0xf bound_ctrl:1
	v_add_f32_dpp v137, v137, v137 row_ror:4 row_mask:0xf bank_mask:0xa
	v_add_f32_dpp v137, v133, v133 row_ror:12 row_mask:0xf bank_mask:0x5
	v_add_f32_dpp v12, v12, v12 row_ror:8 row_mask:0xf bank_mask:0xf bound_ctrl:1
	v_pk_fma_f32 v[6:7], v[40:41], v[12:13], v[48:49] op_sel_hi:[1,0,1] neg_lo:[1,0,0] neg_hi:[1,0,0]
	v_pk_fma_f32 v[8:9], v[42:43], v[12:13], v[50:51] op_sel_hi:[1,0,1] neg_lo:[1,0,0] neg_hi:[1,0,0]
	ds_read_b128 v[188:191], v10 offset:47360
	ds_read_b128 v[196:199], v10 offset:47872
	ds_read_b128 v[192:195], v10 offset:47616
	v_fma_mix_f32 v12, v6, v88, v180 op_sel_hi:[0,1,0]
	v_fma_mix_f32 v12, v7, v88, v12 op_sel:[0,1,0] op_sel_hi:[0,1,0]
	v_fma_mix_f32 v12, v8, v89, v12 op_sel_hi:[0,1,0]
	v_fma_mix_f32 v12, v9, v89, v12 op_sel:[0,1,0] op_sel_hi:[0,1,0]
	v_fma_mix_f32 v100, v6, v38, v180 op_sel_hi:[0,1,0]
	v_fma_mix_f32 v100, v7, v38, v100 op_sel:[0,1,0] op_sel_hi:[0,1,0]
	v_add_f32_dpp v12, v12, v12 row_ror:1 row_mask:0xf bank_mask:0xf bound_ctrl:1
	v_fma_mix_f32 v100, v8, v39, v100 op_sel_hi:[0,1,0]
	v_fma_mix_f32 v100, v9, v39, v100 op_sel:[0,1,0] op_sel_hi:[0,1,0]
	v_add_f32_dpp v12, v12, v12 row_ror:2 row_mask:0xf bank_mask:0xf bound_ctrl:1
	v_pk_fma_f32 v[48:49], v[96:97], v[68:69], v[6:7] op_sel_hi:[1,0,1]
	v_pk_fma_f32 v[50:51], v[98:99], v[68:69], v[8:9] op_sel_hi:[1,0,1]
	v_add_f32_dpp v12, v12, v12 row_ror:4 row_mask:0xf bank_mask:0xf bound_ctrl:1
	v_cndmask_b32_e64 v62, v136, v134, s[38:39]
	v_cndmask_b32_e64 v63, v134, v136, s[38:39]
	v_add_f32_dpp v12, v12, v12 row_ror:8 row_mask:0xf bank_mask:0xf bound_ctrl:1
	v_pk_fma_f32 v[6:7], v[92:93], v[12:13], v[48:49] op_sel_hi:[1,0,1] neg_lo:[1,0,0] neg_hi:[1,0,0]
	v_pk_fma_f32 v[8:9], v[94:95], v[12:13], v[50:51] op_sel_hi:[1,0,1] neg_lo:[1,0,0] neg_hi:[1,0,0]
	ds_read_b128 v[204:207], v10 offset:48384
	ds_read_b128 v[200:203], v10 offset:48128
	ds_read_b128 v[212:215], v10 offset:48896
	ds_read_b128 v[208:211], v10 offset:48640
	v_fma_mix_f32 v12, v6, v110, v180 op_sel_hi:[0,1,0]
	v_fma_mix_f32 v12, v7, v110, v12 op_sel:[0,1,0] op_sel_hi:[0,1,0]
	v_fma_mix_f32 v12, v8, v111, v12 op_sel_hi:[0,1,0]
	v_fma_mix_f32 v12, v9, v111, v12 op_sel:[0,1,0] op_sel_hi:[0,1,0]
	v_fma_mix_f32 v101, v6, v90, v180 op_sel_hi:[0,1,0]
	v_fma_mix_f32 v101, v7, v90, v101 op_sel:[0,1,0] op_sel_hi:[0,1,0]
	v_add_f32_dpp v12, v12, v12 row_ror:1 row_mask:0xf bank_mask:0xf bound_ctrl:1
	v_fma_mix_f32 v101, v8, v91, v101 op_sel_hi:[0,1,0]
	v_fma_mix_f32 v101, v9, v91, v101 op_sel:[0,1,0] op_sel_hi:[0,1,0]
	v_add_f32_dpp v12, v12, v12 row_ror:2 row_mask:0xf bank_mask:0xf bound_ctrl:1
	v_pk_fma_f32 v[48:49], v[118:119], v[68:69], v[6:7] op_sel:[0,1,0]
	v_pk_fma_f32 v[50:51], v[120:121], v[68:69], v[8:9] op_sel:[0,1,0]
	v_add_f32_dpp v12, v12, v12 row_ror:4 row_mask:0xf bank_mask:0xf bound_ctrl:1
	v_cndmask_b32_e64 v64, v137, v135, s[38:39]
	v_cndmask_b32_e64 v65, v135, v137, s[38:39]
	v_add_f32_dpp v12, v12, v12 row_ror:8 row_mask:0xf bank_mask:0xf bound_ctrl:1
	v_pk_fma_f32 v[6:7], v[114:115], v[12:13], v[48:49] op_sel_hi:[1,0,1] neg_lo:[1,0,0] neg_hi:[1,0,0]
	v_pk_fma_f32 v[8:9], v[116:117], v[12:13], v[50:51] op_sel_hi:[1,0,1] neg_lo:[1,0,0] neg_hi:[1,0,0]
	v_pk_mul_f32 v[6:7], v[6:7], v[106:107]
	v_pk_mul_f32 v[8:9], v[8:9], v[108:109]
	s_waitcnt lgkmcnt(0)
	s_nop 0
	ds_read_b128 v[20:23], v10 offset:49408
	ds_read_b128 v[28:31], v10 offset:49920
	ds_read_b128 v[24:27], v10 offset:49664
	v_fma_mix_f32 v12, v6, v142, v180 op_sel_hi:[0,1,0]
	v_fma_mix_f32 v12, v7, v142, v12 op_sel:[0,1,0] op_sel_hi:[0,1,0]
	v_fma_mix_f32 v12, v8, v143, v12 op_sel_hi:[0,1,0]
	v_fma_mix_f32 v12, v9, v143, v12 op_sel:[0,1,0] op_sel_hi:[0,1,0]
	v_fma_mix_f32 v102, v6, v112, v180 op_sel_hi:[0,1,0]
	v_fma_mix_f32 v102, v7, v112, v102 op_sel:[0,1,0] op_sel_hi:[0,1,0]
	v_add_f32_dpp v12, v12, v12 row_ror:1 row_mask:0xf bank_mask:0xf bound_ctrl:1
	v_fma_mix_f32 v102, v8, v113, v102 op_sel_hi:[0,1,0]
	v_fma_mix_f32 v102, v9, v113, v102 op_sel:[0,1,0] op_sel_hi:[0,1,0]
	v_add_f32_dpp v12, v12, v12 row_ror:2 row_mask:0xf bank_mask:0xf bound_ctrl:1
	v_pk_fma_f32 v[48:49], v[150:151], v[70:71], v[6:7] op_sel_hi:[1,0,1]
	v_pk_fma_f32 v[50:51], v[152:153], v[70:71], v[8:9] op_sel_hi:[1,0,1]
	v_add_f32_dpp v12, v12, v12 row_ror:4 row_mask:0xf bank_mask:0xf bound_ctrl:1
	v_add_f32_dpp v62, v63, v62 quad_perm:[2,3,0,1] row_mask:0xf bank_mask:0xf bound_ctrl:1
	v_add_f32_dpp v63, v65, v64 quad_perm:[2,3,0,1] row_mask:0xf bank_mask:0xf bound_ctrl:1
	v_add_f32_dpp v12, v12, v12 row_ror:8 row_mask:0xf bank_mask:0xf bound_ctrl:1
	v_pk_fma_f32 v[6:7], v[146:147], v[12:13], v[48:49] op_sel_hi:[1,0,1] neg_lo:[1,0,0] neg_hi:[1,0,0]
	v_pk_fma_f32 v[8:9], v[148:149], v[12:13], v[50:51] op_sel_hi:[1,0,1] neg_lo:[1,0,0] neg_hi:[1,0,0]
	ds_read_b128 v[36:39], v10 offset:50432
	ds_read_b128 v[44:47], v10 offset:50944
	ds_read_b128 v[40:43], v10 offset:50688
	ds_read_b128 v[66:69], v11 offset:3072
	v_fma_mix_f32 v12, v6, v158, v180 op_sel_hi:[0,1,0]
	v_fma_mix_f32 v12, v7, v158, v12 op_sel:[0,1,0] op_sel_hi:[0,1,0]
	v_fma_mix_f32 v12, v8, v159, v12 op_sel_hi:[0,1,0]
	v_fma_mix_f32 v12, v9, v159, v12 op_sel:[0,1,0] op_sel_hi:[0,1,0]
	v_fma_mix_f32 v103, v6, v144, v180 op_sel_hi:[0,1,0]
	v_fma_mix_f32 v103, v7, v144, v103 op_sel:[0,1,0] op_sel_hi:[0,1,0]
	v_add_f32_dpp v12, v12, v12 row_ror:1 row_mask:0xf bank_mask:0xf bound_ctrl:1
	v_fma_mix_f32 v103, v8, v145, v103 op_sel_hi:[0,1,0]
	v_fma_mix_f32 v103, v9, v145, v103 op_sel:[0,1,0] op_sel_hi:[0,1,0]
	v_add_f32_dpp v12, v12, v12 row_ror:2 row_mask:0xf bank_mask:0xf bound_ctrl:1
	v_pk_fma_f32 v[48:49], v[166:167], v[70:71], v[6:7] op_sel:[0,1,0]
	v_pk_fma_f32 v[50:51], v[168:169], v[70:71], v[8:9] op_sel:[0,1,0]
	v_add_f32_dpp v12, v12, v12 row_ror:4 row_mask:0xf bank_mask:0xf bound_ctrl:1
	v_cndmask_b32_e64 v65, v63, v62, s[40:41]
	v_cndmask_b32_e64 v62, v62, v63, s[40:41]
	v_add_f32_dpp v12, v12, v12 row_ror:8 row_mask:0xf bank_mask:0xf bound_ctrl:1
	v_pk_fma_f32 v[6:7], v[162:163], v[12:13], v[48:49] op_sel_hi:[1,0,1] neg_lo:[1,0,0] neg_hi:[1,0,0]
	v_pk_fma_f32 v[8:9], v[164:165], v[12:13], v[50:51] op_sel_hi:[1,0,1] neg_lo:[1,0,0] neg_hi:[1,0,0]
	ds_read_b128 v[88:91], v10 offset:51456
	ds_read_b128 v[96:99], v10 offset:51968
	ds_read_b128 v[92:95], v10 offset:51712
	v_fma_mix_f32 v12, v6, v188, v180 op_sel_hi:[0,1,0]
	v_fma_mix_f32 v12, v7, v188, v12 op_sel:[0,1,0] op_sel_hi:[0,1,0]
	v_fma_mix_f32 v12, v8, v189, v12 op_sel_hi:[0,1,0]
	v_fma_mix_f32 v12, v9, v189, v12 op_sel:[0,1,0] op_sel_hi:[0,1,0]
	v_fma_mix_f32 v104, v6, v160, v180 op_sel_hi:[0,1,0]
	v_fma_mix_f32 v104, v7, v160, v104 op_sel:[0,1,0] op_sel_hi:[0,1,0]
	v_add_f32_dpp v12, v12, v12 row_ror:1 row_mask:0xf bank_mask:0xf bound_ctrl:1
	v_fma_mix_f32 v104, v8, v161, v104 op_sel_hi:[0,1,0]
	v_fma_mix_f32 v104, v9, v161, v104 op_sel:[0,1,0] op_sel_hi:[0,1,0]
	v_add_f32_dpp v12, v12, v12 row_ror:2 row_mask:0xf bank_mask:0xf bound_ctrl:1
	v_pk_fma_f32 v[48:49], v[196:197], v[72:73], v[6:7] op_sel_hi:[1,0,1]
	v_pk_fma_f32 v[50:51], v[198:199], v[72:73], v[8:9] op_sel_hi:[1,0,1]
	v_add_f32_dpp v12, v12, v12 row_ror:4 row_mask:0xf bank_mask:0xf bound_ctrl:1
	v_add_f32_dpp v62, v62, v65 quad_perm:[1,0,3,2] row_mask:0xf bank_mask:0xf bound_ctrl:1
	v_cvt_pk_bf16_f32 v62, v62, v62
	v_add_f32_dpp v12, v12, v12 row_ror:8 row_mask:0xf bank_mask:0xf bound_ctrl:1
	v_pk_fma_f32 v[6:7], v[192:193], v[12:13], v[48:49] op_sel_hi:[1,0,1] neg_lo:[1,0,0] neg_hi:[1,0,0]
	v_pk_fma_f32 v[8:9], v[194:195], v[12:13], v[50:51] op_sel_hi:[1,0,1] neg_lo:[1,0,0] neg_hi:[1,0,0]
	ds_read_b128 v[110:113], v10 offset:52480
	ds_read_b128 v[106:109], v10 offset:52224
	ds_read_b128 v[118:121], v10 offset:52992
	ds_read_b128 v[114:117], v10 offset:52736
	v_fma_mix_f32 v12, v6, v204, v180 op_sel_hi:[0,1,0]
	v_fma_mix_f32 v12, v7, v204, v12 op_sel:[0,1,0] op_sel_hi:[0,1,0]
	v_fma_mix_f32 v12, v8, v205, v12 op_sel_hi:[0,1,0]
	v_fma_mix_f32 v12, v9, v205, v12 op_sel:[0,1,0] op_sel_hi:[0,1,0]
	v_fma_mix_f32 v105, v6, v190, v180 op_sel_hi:[0,1,0]
	v_fma_mix_f32 v105, v7, v190, v105 op_sel:[0,1,0] op_sel_hi:[0,1,0]
	v_add_f32_dpp v12, v12, v12 row_ror:1 row_mask:0xf bank_mask:0xf bound_ctrl:1
	v_fma_mix_f32 v105, v8, v191, v105 op_sel_hi:[0,1,0]
	v_fma_mix_f32 v105, v9, v191, v105 op_sel:[0,1,0] op_sel_hi:[0,1,0]
	v_add_f32_dpp v12, v12, v12 row_ror:2 row_mask:0xf bank_mask:0xf bound_ctrl:1
	v_pk_fma_f32 v[48:49], v[212:213], v[72:73], v[6:7] op_sel:[0,1,0]
	v_pk_fma_f32 v[50:51], v[214:215], v[72:73], v[8:9] op_sel:[0,1,0]
	v_add_f32_dpp v12, v12, v12 row_ror:4 row_mask:0xf bank_mask:0xf bound_ctrl:1
	global_store_short v[2:3], v62, off
	v_lshl_add_u64 v[2:3], v[2:3], 0, s[84:85]
	v_add_f32_dpp v12, v12, v12 row_ror:8 row_mask:0xf bank_mask:0xf bound_ctrl:1
	v_pk_fma_f32 v[6:7], v[208:209], v[12:13], v[48:49] op_sel_hi:[1,0,1] neg_lo:[1,0,0] neg_hi:[1,0,0]
	v_pk_fma_f32 v[8:9], v[210:211], v[12:13], v[50:51] op_sel_hi:[1,0,1] neg_lo:[1,0,0] neg_hi:[1,0,0]
	v_pk_mul_f32 v[6:7], v[6:7], v[200:201]
	v_pk_mul_f32 v[8:9], v[8:9], v[202:203]
	s_waitcnt lgkmcnt(0)
	s_nop 0
	ds_read_b128 v[142:145], v10 offset:53504
	ds_read_b128 v[150:153], v10 offset:54016
	ds_read_b128 v[146:149], v10 offset:53760
	v_fma_mix_f32 v12, v6, v20, v180 op_sel_hi:[0,1,0]
	v_fma_mix_f32 v12, v7, v20, v12 op_sel:[0,1,0] op_sel_hi:[0,1,0]
	v_fma_mix_f32 v12, v8, v21, v12 op_sel_hi:[0,1,0]
	v_fma_mix_f32 v12, v9, v21, v12 op_sel:[0,1,0] op_sel_hi:[0,1,0]
	v_fma_mix_f32 v61, v6, v206, v180 op_sel_hi:[0,1,0]
	v_fma_mix_f32 v61, v7, v206, v61 op_sel:[0,1,0] op_sel_hi:[0,1,0]
	v_add_f32_dpp v12, v12, v12 row_ror:1 row_mask:0xf bank_mask:0xf bound_ctrl:1
	v_fma_mix_f32 v61, v8, v207, v61 op_sel_hi:[0,1,0]
	v_fma_mix_f32 v61, v9, v207, v61 op_sel:[0,1,0] op_sel_hi:[0,1,0]
	v_add_f32_dpp v12, v12, v12 row_ror:2 row_mask:0xf bank_mask:0xf bound_ctrl:1
	v_pk_fma_f32 v[48:49], v[28:29], v[66:67], v[6:7] op_sel_hi:[1,0,1]
	v_pk_fma_f32 v[50:51], v[30:31], v[66:67], v[8:9] op_sel_hi:[1,0,1]
	v_add_f32_dpp v12, v12, v12 row_ror:4 row_mask:0xf bank_mask:0xf bound_ctrl:1
	s_nop 1
	s_nop 0
	v_add_f32_dpp v12, v12, v12 row_ror:8 row_mask:0xf bank_mask:0xf bound_ctrl:1
	v_pk_fma_f32 v[6:7], v[24:25], v[12:13], v[48:49] op_sel_hi:[1,0,1] neg_lo:[1,0,0] neg_hi:[1,0,0]
	v_pk_fma_f32 v[8:9], v[26:27], v[12:13], v[50:51] op_sel_hi:[1,0,1] neg_lo:[1,0,0] neg_hi:[1,0,0]
	ds_read_b128 v[158:161], v10 offset:54528
	ds_read_b128 v[166:169], v10 offset:55040
	ds_read_b128 v[162:165], v10 offset:54784
	ds_read_b128 v[70:73], v11 offset:3328
	v_fma_mix_f32 v12, v6, v36, v180 op_sel_hi:[0,1,0]
	v_fma_mix_f32 v12, v7, v36, v12 op_sel:[0,1,0] op_sel_hi:[0,1,0]
	v_fma_mix_f32 v12, v8, v37, v12 op_sel_hi:[0,1,0]
	v_fma_mix_f32 v12, v9, v37, v12 op_sel:[0,1,0] op_sel_hi:[0,1,0]
	v_fma_mix_f32 v122, v6, v22, v180 op_sel_hi:[0,1,0]
	v_fma_mix_f32 v122, v7, v22, v122 op_sel:[0,1,0] op_sel_hi:[0,1,0]
	v_add_f32_dpp v12, v12, v12 row_ror:1 row_mask:0xf bank_mask:0xf bound_ctrl:1
	v_fma_mix_f32 v122, v8, v23, v122 op_sel_hi:[0,1,0]
	v_fma_mix_f32 v122, v9, v23, v122 op_sel:[0,1,0] op_sel_hi:[0,1,0]
	v_add_f32_dpp v12, v12, v12 row_ror:2 row_mask:0xf bank_mask:0xf bound_ctrl:1
	v_pk_fma_f32 v[48:49], v[44:45], v[66:67], v[6:7] op_sel:[0,1,0]
	v_pk_fma_f32 v[50:51], v[46:47], v[66:67], v[8:9] op_sel:[0,1,0]
	v_add_f32_dpp v12, v12, v12 row_ror:4 row_mask:0xf bank_mask:0xf bound_ctrl:1
	v_add_f32_dpp v83, v83, v83 row_ror:8 row_mask:0xf bank_mask:0xc
	v_add_f32_dpp v83, v52, v52 row_ror:8 row_mask:0xf bank_mask:0x3
	v_add_f32_dpp v100, v100, v100 row_ror:8 row_mask:0xf bank_mask:0xc
	v_add_f32_dpp v12, v12, v12 row_ror:8 row_mask:0xf bank_mask:0xf bound_ctrl:1
	v_pk_fma_f32 v[6:7], v[40:41], v[12:13], v[48:49] op_sel_hi:[1,0,1] neg_lo:[1,0,0] neg_hi:[1,0,0]
	v_pk_fma_f32 v[8:9], v[42:43], v[12:13], v[50:51] op_sel_hi:[1,0,1] neg_lo:[1,0,0] neg_hi:[1,0,0]
	ds_read_b128 v[188:191], v10 offset:55552
	ds_read_b128 v[196:199], v10 offset:56064
	ds_read_b128 v[192:195], v10 offset:55808
	v_fma_mix_f32 v12, v6, v88, v180 op_sel_hi:[0,1,0]
	v_fma_mix_f32 v12, v7, v88, v12 op_sel:[0,1,0] op_sel_hi:[0,1,0]
	v_fma_mix_f32 v12, v8, v89, v12 op_sel_hi:[0,1,0]
	v_fma_mix_f32 v12, v9, v89, v12 op_sel:[0,1,0] op_sel_hi:[0,1,0]
	v_fma_mix_f32 v123, v6, v38, v180 op_sel_hi:[0,1,0]
	v_fma_mix_f32 v123, v7, v38, v123 op_sel:[0,1,0] op_sel_hi:[0,1,0]
	v_add_f32_dpp v12, v12, v12 row_ror:1 row_mask:0xf bank_mask:0xf bound_ctrl:1
	v_fma_mix_f32 v123, v8, v39, v123 op_sel_hi:[0,1,0]
	v_fma_mix_f32 v123, v9, v39, v123 op_sel:[0,1,0] op_sel_hi:[0,1,0]
	v_add_f32_dpp v12, v12, v12 row_ror:2 row_mask:0xf bank_mask:0xf bound_ctrl:1
	v_pk_fma_f32 v[48:49], v[96:97], v[68:69], v[6:7] op_sel_hi:[1,0,1]
	v_pk_fma_f32 v[50:51], v[98:99], v[68:69], v[8:9] op_sel_hi:[1,0,1]
	v_add_f32_dpp v12, v12, v12 row_ror:4 row_mask:0xf bank_mask:0xf bound_ctrl:1
	v_add_f32_dpp v100, v53, v53 row_ror:8 row_mask:0xf bank_mask:0x3
	v_add_f32_dpp v101, v101, v101 row_ror:8 row_mask:0xf bank_mask:0xc
	v_add_f32_dpp v101, v54, v54 row_ror:8 row_mask:0xf bank_mask:0x3
	v_add_f32_dpp v12, v12, v12 row_ror:8 row_mask:0xf bank_mask:0xf bound_ctrl:1
	v_pk_fma_f32 v[6:7], v[92:93], v[12:13], v[48:49] op_sel_hi:[1,0,1] neg_lo:[1,0,0] neg_hi:[1,0,0]
	v_pk_fma_f32 v[8:9], v[94:95], v[12:13], v[50:51] op_sel_hi:[1,0,1] neg_lo:[1,0,0] neg_hi:[1,0,0]
	ds_read_b128 v[204:207], v10 offset:56576
	ds_read_b128 v[200:203], v10 offset:56320
	ds_read_b128 v[212:215], v10 offset:57088
	ds_read_b128 v[208:211], v10 offset:56832
	v_fma_mix_f32 v12, v6, v110, v180 op_sel_hi:[0,1,0]
	v_fma_mix_f32 v12, v7, v110, v12 op_sel:[0,1,0] op_sel_hi:[0,1,0]
	v_fma_mix_f32 v12, v8, v111, v12 op_sel_hi:[0,1,0]
	v_fma_mix_f32 v12, v9, v111, v12 op_sel:[0,1,0] op_sel_hi:[0,1,0]
	v_fma_mix_f32 v124, v6, v90, v180 op_sel_hi:[0,1,0]
	v_fma_mix_f32 v124, v7, v90, v124 op_sel:[0,1,0] op_sel_hi:[0,1,0]
	v_add_f32_dpp v12, v12, v12 row_ror:1 row_mask:0xf bank_mask:0xf bound_ctrl:1
	v_fma_mix_f32 v124, v8, v91, v124 op_sel_hi:[0,1,0]
	v_fma_mix_f32 v124, v9, v91, v124 op_sel:[0,1,0] op_sel_hi:[0,1,0]
	v_add_f32_dpp v12, v12, v12 row_ror:2 row_mask:0xf bank_mask:0xf bound_ctrl:1
	v_pk_fma_f32 v[48:49], v[118:119], v[68:69], v[6:7] op_sel:[0,1,0]
	v_pk_fma_f32 v[50:51], v[120:121], v[68:69], v[8:9] op_sel:[0,1,0]
	v_add_f32_dpp v12, v12, v12 row_ror:4 row_mask:0xf bank_mask:0xf bound_ctrl:1
	v_add_f32_dpp v102, v102, v102 row_ror:8 row_mask:0xf bank_mask:0xc
	v_add_f32_dpp v102, v55, v55 row_ror:8 row_mask:0xf bank_mask:0x3
	v_add_f32_dpp v103, v103, v103 row_ror:8 row_mask:0xf bank_mask:0xc
	v_add_f32_dpp v12, v12, v12 row_ror:8 row_mask:0xf bank_mask:0xf bound_ctrl:1
	v_pk_fma_f32 v[6:7], v[114:115], v[12:13], v[48:49] op_sel_hi:[1,0,1] neg_lo:[1,0,0] neg_hi:[1,0,0]
	v_pk_fma_f32 v[8:9], v[116:117], v[12:13], v[50:51] op_sel_hi:[1,0,1] neg_lo:[1,0,0] neg_hi:[1,0,0]
	v_pk_mul_f32 v[6:7], v[6:7], v[106:107]
	v_pk_mul_f32 v[8:9], v[8:9], v[108:109]
	s_waitcnt lgkmcnt(0)
	s_nop 0
	ds_read_b128 v[20:23], v10 offset:57600
	ds_read_b128 v[28:31], v10 offset:58112
	ds_read_b128 v[24:27], v10 offset:57856
	v_fma_mix_f32 v12, v6, v142, v180 op_sel_hi:[0,1,0]
	v_fma_mix_f32 v12, v7, v142, v12 op_sel:[0,1,0] op_sel_hi:[0,1,0]
	v_fma_mix_f32 v12, v8, v143, v12 op_sel_hi:[0,1,0]
	v_fma_mix_f32 v12, v9, v143, v12 op_sel:[0,1,0] op_sel_hi:[0,1,0]
	v_fma_mix_f32 v125, v6, v112, v180 op_sel_hi:[0,1,0]
	v_fma_mix_f32 v125, v7, v112, v125 op_sel:[0,1,0] op_sel_hi:[0,1,0]
	v_add_f32_dpp v12, v12, v12 row_ror:1 row_mask:0xf bank_mask:0xf bound_ctrl:1
	v_fma_mix_f32 v125, v8, v113, v125 op_sel_hi:[0,1,0]
	v_fma_mix_f32 v125, v9, v113, v125 op_sel:[0,1,0] op_sel_hi:[0,1,0]
	v_add_f32_dpp v12, v12, v12 row_ror:2 row_mask:0xf bank_mask:0xf bound_ctrl:1
	v_pk_fma_f32 v[48:49], v[150:151], v[70:71], v[6:7] op_sel_hi:[1,0,1]
	v_pk_fma_f32 v[50:51], v[152:153], v[70:71], v[8:9] op_sel_hi:[1,0,1]
	v_add_f32_dpp v12, v12, v12 row_ror:4 row_mask:0xf bank_mask:0xf bound_ctrl:1
	v_add_f32_dpp v103, v56, v56 row_ror:8 row_mask:0xf bank_mask:0x3
	v_add_f32_dpp v104, v104, v104 row_ror:8 row_mask:0xf bank_mask:0xc
	v_add_f32_dpp v104, v57, v57 row_ror:8 row_mask:0xf bank_mask:0x3
	v_add_f32_dpp v12, v12, v12 row_ror:8 row_mask:0xf bank_mask:0xf bound_ctrl:1
	v_pk_fma_f32 v[6:7], v[146:147], v[12:13], v[48:49] op_sel_hi:[1,0,1] neg_lo:[1,0,0] neg_hi:[1,0,0]
	v_pk_fma_f32 v[8:9], v[148:149], v[12:13], v[50:51] op_sel_hi:[1,0,1] neg_lo:[1,0,0] neg_hi:[1,0,0]
	ds_read_b128 v[36:39], v10 offset:58624
	ds_read_b128 v[44:47], v10 offset:59136
	ds_read_b128 v[40:43], v10 offset:58880
	ds_read_b128 v[66:69], v11 offset:3584
	v_fma_mix_f32 v12, v6, v158, v180 op_sel_hi:[0,1,0]
	v_fma_mix_f32 v12, v7, v158, v12 op_sel:[0,1,0] op_sel_hi:[0,1,0]
	v_fma_mix_f32 v12, v8, v159, v12 op_sel_hi:[0,1,0]
	v_fma_mix_f32 v12, v9, v159, v12 op_sel:[0,1,0] op_sel_hi:[0,1,0]
	v_fma_mix_f32 v126, v6, v144, v180 op_sel_hi:[0,1,0]
	v_fma_mix_f32 v126, v7, v144, v126 op_sel:[0,1,0] op_sel_hi:[0,1,0]
	v_add_f32_dpp v12, v12, v12 row_ror:1 row_mask:0xf bank_mask:0xf bound_ctrl:1
	v_fma_mix_f32 v126, v8, v145, v126 op_sel_hi:[0,1,0]
	v_fma_mix_f32 v126, v9, v145, v126 op_sel:[0,1,0] op_sel_hi:[0,1,0]
	v_add_f32_dpp v12, v12, v12 row_ror:2 row_mask:0xf bank_mask:0xf bound_ctrl:1
	v_pk_fma_f32 v[48:49], v[166:167], v[70:71], v[6:7] op_sel:[0,1,0]
	v_pk_fma_f32 v[50:51], v[168:169], v[70:71], v[8:9] op_sel:[0,1,0]
	v_add_f32_dpp v12, v12, v12 row_ror:4 row_mask:0xf bank_mask:0xf bound_ctrl:1
	v_add_f32_dpp v105, v105, v105 row_ror:8 row_mask:0xf bank_mask:0xc
	v_add_f32_dpp v105, v81, v81 row_ror:8 row_mask:0xf bank_mask:0x3
	v_add_f32_dpp v12, v12, v12 row_ror:8 row_mask:0xf bank_mask:0xf bound_ctrl:1
	v_pk_fma_f32 v[6:7], v[162:163], v[12:13], v[48:49] op_sel_hi:[1,0,1] neg_lo:[1,0,0] neg_hi:[1,0,0]
	v_pk_fma_f32 v[8:9], v[164:165], v[12:13], v[50:51] op_sel_hi:[1,0,1] neg_lo:[1,0,0] neg_hi:[1,0,0]
	ds_read_b128 v[88:91], v10 offset:59648
	ds_read_b128 v[96:99], v10 offset:60160
	ds_read_b128 v[92:95], v10 offset:59904
	v_fma_mix_f32 v12, v6, v188, v180 op_sel_hi:[0,1,0]
	v_fma_mix_f32 v12, v7, v188, v12 op_sel:[0,1,0] op_sel_hi:[0,1,0]
	v_fma_mix_f32 v12, v8, v189, v12 op_sel_hi:[0,1,0]
	v_fma_mix_f32 v12, v9, v189, v12 op_sel:[0,1,0] op_sel_hi:[0,1,0]
	v_fma_mix_f32 v127, v6, v160, v180 op_sel_hi:[0,1,0]
	v_fma_mix_f32 v127, v7, v160, v127 op_sel:[0,1,0] op_sel_hi:[0,1,0]
	v_add_f32_dpp v12, v12, v12 row_ror:1 row_mask:0xf bank_mask:0xf bound_ctrl:1
	v_fma_mix_f32 v127, v8, v161, v127 op_sel_hi:[0,1,0]
	v_fma_mix_f32 v127, v9, v161, v127 op_sel:[0,1,0] op_sel_hi:[0,1,0]
	v_add_f32_dpp v12, v12, v12 row_ror:2 row_mask:0xf bank_mask:0xf bound_ctrl:1
	v_pk_fma_f32 v[48:49], v[196:197], v[72:73], v[6:7] op_sel_hi:[1,0,1]
	v_pk_fma_f32 v[50:51], v[198:199], v[72:73], v[8:9] op_sel_hi:[1,0,1]
	v_add_f32_dpp v12, v12, v12 row_ror:4 row_mask:0xf bank_mask:0xf bound_ctrl:1
	v_add_f32_dpp v61, v61, v61 row_ror:8 row_mask:0xf bank_mask:0xc
	v_add_f32_dpp v61, v82, v82 row_ror:8 row_mask:0xf bank_mask:0x3
	v_add_f32_dpp v12, v12, v12 row_ror:8 row_mask:0xf bank_mask:0xf bound_ctrl:1
	v_pk_fma_f32 v[6:7], v[192:193], v[12:13], v[48:49] op_sel_hi:[1,0,1] neg_lo:[1,0,0] neg_hi:[1,0,0]
	v_pk_fma_f32 v[8:9], v[194:195], v[12:13], v[50:51] op_sel_hi:[1,0,1] neg_lo:[1,0,0] neg_hi:[1,0,0]
	ds_read_b128 v[110:113], v10 offset:60672
	ds_read_b128 v[106:109], v10 offset:60416
	ds_read_b128 v[118:121], v10 offset:61184
	ds_read_b128 v[114:117], v10 offset:60928
	v_fma_mix_f32 v12, v6, v204, v180 op_sel_hi:[0,1,0]
	v_fma_mix_f32 v12, v7, v204, v12 op_sel:[0,1,0] op_sel_hi:[0,1,0]
	v_fma_mix_f32 v12, v8, v205, v12 op_sel_hi:[0,1,0]
	v_fma_mix_f32 v12, v9, v205, v12 op_sel:[0,1,0] op_sel_hi:[0,1,0]
	v_fma_mix_f32 v128, v6, v190, v180 op_sel_hi:[0,1,0]
	v_fma_mix_f32 v128, v7, v190, v128 op_sel:[0,1,0] op_sel_hi:[0,1,0]
	v_add_f32_dpp v12, v12, v12 row_ror:1 row_mask:0xf bank_mask:0xf bound_ctrl:1
	v_fma_mix_f32 v128, v8, v191, v128 op_sel_hi:[0,1,0]
	v_fma_mix_f32 v128, v9, v191, v128 op_sel:[0,1,0] op_sel_hi:[0,1,0]
	v_add_f32_dpp v12, v12, v12 row_ror:2 row_mask:0xf bank_mask:0xf bound_ctrl:1
	v_pk_fma_f32 v[48:49], v[212:213], v[72:73], v[6:7] op_sel:[0,1,0]
	v_pk_fma_f32 v[50:51], v[214:215], v[72:73], v[8:9] op_sel:[0,1,0]
	v_add_f32_dpp v12, v12, v12 row_ror:4 row_mask:0xf bank_mask:0xf bound_ctrl:1
	v_add_f32_dpp v103, v103, v103 row_ror:4 row_mask:0xf bank_mask:0xa
	v_add_f32_dpp v103, v83, v83 row_ror:12 row_mask:0xf bank_mask:0x5
	v_add_f32_dpp v104, v104, v104 row_ror:4 row_mask:0xf bank_mask:0xa
	v_add_f32_dpp v12, v12, v12 row_ror:8 row_mask:0xf bank_mask:0xf bound_ctrl:1
	v_pk_fma_f32 v[6:7], v[208:209], v[12:13], v[48:49] op_sel_hi:[1,0,1] neg_lo:[1,0,0] neg_hi:[1,0,0]
	v_pk_fma_f32 v[8:9], v[210:211], v[12:13], v[50:51] op_sel_hi:[1,0,1] neg_lo:[1,0,0] neg_hi:[1,0,0]
	v_pk_mul_f32 v[6:7], v[6:7], v[200:201]
	v_pk_mul_f32 v[8:9], v[8:9], v[202:203]
	s_waitcnt lgkmcnt(0)
	s_nop 0
	ds_read_b128 v[142:145], v10 offset:61696
	ds_read_b128 v[150:153], v10 offset:62208
	ds_read_b128 v[146:149], v10 offset:61952
	v_fma_mix_f32 v12, v6, v20, v180 op_sel_hi:[0,1,0]
	v_fma_mix_f32 v12, v7, v20, v12 op_sel:[0,1,0] op_sel_hi:[0,1,0]
	v_fma_mix_f32 v12, v8, v21, v12 op_sel_hi:[0,1,0]
	v_fma_mix_f32 v12, v9, v21, v12 op_sel:[0,1,0] op_sel_hi:[0,1,0]
	v_fma_mix_f32 v129, v6, v206, v180 op_sel_hi:[0,1,0]
	v_fma_mix_f32 v129, v7, v206, v129 op_sel:[0,1,0] op_sel_hi:[0,1,0]
	v_add_f32_dpp v12, v12, v12 row_ror:1 row_mask:0xf bank_mask:0xf bound_ctrl:1
	v_fma_mix_f32 v129, v8, v207, v129 op_sel_hi:[0,1,0]
	v_fma_mix_f32 v129, v9, v207, v129 op_sel:[0,1,0] op_sel_hi:[0,1,0]
	v_add_f32_dpp v12, v12, v12 row_ror:2 row_mask:0xf bank_mask:0xf bound_ctrl:1
	v_pk_fma_f32 v[48:49], v[28:29], v[66:67], v[6:7] op_sel_hi:[1,0,1]
	v_pk_fma_f32 v[50:51], v[30:31], v[66:67], v[8:9] op_sel_hi:[1,0,1]
	v_add_f32_dpp v12, v12, v12 row_ror:4 row_mask:0xf bank_mask:0xf bound_ctrl:1
	v_add_f32_dpp v104, v100, v100 row_ror:12 row_mask:0xf bank_mask:0x5
	v_add_f32_dpp v105, v105, v105 row_ror:4 row_mask:0xf bank_mask:0xa
	v_add_f32_dpp v105, v101, v101 row_ror:12 row_mask:0xf bank_mask:0x5
	v_add_f32_dpp v12, v12, v12 row_ror:8 row_mask:0xf bank_mask:0xf bound_ctrl:1
	v_pk_fma_f32 v[6:7], v[24:25], v[12:13], v[48:49] op_sel_hi:[1,0,1] neg_lo:[1,0,0] neg_hi:[1,0,0]
	v_pk_fma_f32 v[8:9], v[26:27], v[12:13], v[50:51] op_sel_hi:[1,0,1] neg_lo:[1,0,0] neg_hi:[1,0,0]
	ds_read_b128 v[158:161], v10 offset:62720
	ds_read_b128 v[166:169], v10 offset:63232
	ds_read_b128 v[162:165], v10 offset:62976
	ds_read_b128 v[70:73], v11 offset:3840
	v_fma_mix_f32 v12, v6, v36, v180 op_sel_hi:[0,1,0]
	v_fma_mix_f32 v12, v7, v36, v12 op_sel:[0,1,0] op_sel_hi:[0,1,0]
	v_fma_mix_f32 v12, v8, v37, v12 op_sel_hi:[0,1,0]
	v_fma_mix_f32 v12, v9, v37, v12 op_sel:[0,1,0] op_sel_hi:[0,1,0]
	v_fma_mix_f32 v130, v6, v22, v180 op_sel_hi:[0,1,0]
	v_fma_mix_f32 v130, v7, v22, v130 op_sel:[0,1,0] op_sel_hi:[0,1,0]
	v_add_f32_dpp v12, v12, v12 row_ror:1 row_mask:0xf bank_mask:0xf bound_ctrl:1
	v_fma_mix_f32 v130, v8, v23, v130 op_sel_hi:[0,1,0]
	v_fma_mix_f32 v130, v9, v23, v130 op_sel:[0,1,0] op_sel_hi:[0,1,0]
	v_add_f32_dpp v12, v12, v12 row_ror:2 row_mask:0xf bank_mask:0xf bound_ctrl:1
	v_pk_fma_f32 v[48:49], v[44:45], v[66:67], v[6:7] op_sel:[0,1,0]
	v_pk_fma_f32 v[50:51], v[46:47], v[66:67], v[8:9] op_sel:[0,1,0]
	v_add_f32_dpp v12, v12, v12 row_ror:4 row_mask:0xf bank_mask:0xf bound_ctrl:1
	v_add_f32_dpp v61, v61, v61 row_ror:4 row_mask:0xf bank_mask:0xa
	v_add_f32_dpp v61, v102, v102 row_ror:12 row_mask:0xf bank_mask:0x5
	v_add_f32_dpp v12, v12, v12 row_ror:8 row_mask:0xf bank_mask:0xf bound_ctrl:1
	v_pk_fma_f32 v[6:7], v[40:41], v[12:13], v[48:49] op_sel_hi:[1,0,1] neg_lo:[1,0,0] neg_hi:[1,0,0]
	v_pk_fma_f32 v[8:9], v[42:43], v[12:13], v[50:51] op_sel_hi:[1,0,1] neg_lo:[1,0,0] neg_hi:[1,0,0]
	ds_read_b128 v[188:191], v10 offset:63744
	ds_read_b128 v[196:199], v10 offset:64256
	ds_read_b128 v[192:195], v10 offset:64000
	v_fma_mix_f32 v12, v6, v88, v180 op_sel_hi:[0,1,0]
	v_fma_mix_f32 v12, v7, v88, v12 op_sel:[0,1,0] op_sel_hi:[0,1,0]
	v_fma_mix_f32 v12, v8, v89, v12 op_sel_hi:[0,1,0]
	v_fma_mix_f32 v12, v9, v89, v12 op_sel:[0,1,0] op_sel_hi:[0,1,0]
	v_fma_mix_f32 v131, v6, v38, v180 op_sel_hi:[0,1,0]
	v_fma_mix_f32 v131, v7, v38, v131 op_sel:[0,1,0] op_sel_hi:[0,1,0]
	v_add_f32_dpp v12, v12, v12 row_ror:1 row_mask:0xf bank_mask:0xf bound_ctrl:1
	v_fma_mix_f32 v131, v8, v39, v131 op_sel_hi:[0,1,0]
	v_fma_mix_f32 v131, v9, v39, v131 op_sel:[0,1,0] op_sel_hi:[0,1,0]
	v_add_f32_dpp v12, v12, v12 row_ror:2 row_mask:0xf bank_mask:0xf bound_ctrl:1
	v_pk_fma_f32 v[48:49], v[96:97], v[68:69], v[6:7] op_sel_hi:[1,0,1]
	v_pk_fma_f32 v[50:51], v[98:99], v[68:69], v[8:9] op_sel_hi:[1,0,1]
	v_add_f32_dpp v12, v12, v12 row_ror:4 row_mask:0xf bank_mask:0xf bound_ctrl:1
	v_cndmask_b32_e64 v62, v105, v103, s[38:39]
	v_cndmask_b32_e64 v63, v103, v105, s[38:39]
	v_add_f32_dpp v12, v12, v12 row_ror:8 row_mask:0xf bank_mask:0xf bound_ctrl:1
	v_pk_fma_f32 v[6:7], v[92:93], v[12:13], v[48:49] op_sel_hi:[1,0,1] neg_lo:[1,0,0] neg_hi:[1,0,0]
	v_pk_fma_f32 v[8:9], v[94:95], v[12:13], v[50:51] op_sel_hi:[1,0,1] neg_lo:[1,0,0] neg_hi:[1,0,0]
	ds_read_b128 v[204:207], v10 offset:64768
	ds_read_b128 v[200:203], v10 offset:64512
	ds_read_b128 v[212:215], v10 offset:65280
	ds_read_b128 v[208:211], v10 offset:65024
	v_fma_mix_f32 v12, v6, v110, v180 op_sel_hi:[0,1,0]
	v_fma_mix_f32 v12, v7, v110, v12 op_sel:[0,1,0] op_sel_hi:[0,1,0]
	v_fma_mix_f32 v12, v8, v111, v12 op_sel_hi:[0,1,0]
	v_fma_mix_f32 v12, v9, v111, v12 op_sel:[0,1,0] op_sel_hi:[0,1,0]
	v_fma_mix_f32 v132, v6, v90, v180 op_sel_hi:[0,1,0]
	v_fma_mix_f32 v132, v7, v90, v132 op_sel:[0,1,0] op_sel_hi:[0,1,0]
	v_add_f32_dpp v12, v12, v12 row_ror:1 row_mask:0xf bank_mask:0xf bound_ctrl:1
	v_fma_mix_f32 v132, v8, v91, v132 op_sel_hi:[0,1,0]
	v_fma_mix_f32 v132, v9, v91, v132 op_sel:[0,1,0] op_sel_hi:[0,1,0]
	v_add_f32_dpp v12, v12, v12 row_ror:2 row_mask:0xf bank_mask:0xf bound_ctrl:1
	v_pk_fma_f32 v[48:49], v[118:119], v[68:69], v[6:7] op_sel:[0,1,0]
	v_pk_fma_f32 v[50:51], v[120:121], v[68:69], v[8:9] op_sel:[0,1,0]
	v_add_f32_dpp v12, v12, v12 row_ror:4 row_mask:0xf bank_mask:0xf bound_ctrl:1
	v_cndmask_b32_e64 v64, v61, v104, s[38:39]
	v_cndmask_b32_e64 v65, v104, v61, s[38:39]
	v_add_f32_dpp v12, v12, v12 row_ror:8 row_mask:0xf bank_mask:0xf bound_ctrl:1
	v_pk_fma_f32 v[6:7], v[114:115], v[12:13], v[48:49] op_sel_hi:[1,0,1] neg_lo:[1,0,0] neg_hi:[1,0,0]
	v_pk_fma_f32 v[8:9], v[116:117], v[12:13], v[50:51] op_sel_hi:[1,0,1] neg_lo:[1,0,0] neg_hi:[1,0,0]
	v_pk_mul_f32 v[6:7], v[6:7], v[106:107]
	v_pk_mul_f32 v[8:9], v[8:9], v[108:109]
	s_waitcnt lgkmcnt(0)
	s_nop 0
	v_fma_mix_f32 v12, v6, v142, v180 op_sel_hi:[0,1,0]
	v_fma_mix_f32 v12, v7, v142, v12 op_sel:[0,1,0] op_sel_hi:[0,1,0]
	v_fma_mix_f32 v12, v8, v143, v12 op_sel_hi:[0,1,0]
	v_fma_mix_f32 v12, v9, v143, v12 op_sel:[0,1,0] op_sel_hi:[0,1,0]
	v_fma_mix_f32 v133, v6, v112, v180 op_sel_hi:[0,1,0]
	v_fma_mix_f32 v133, v7, v112, v133 op_sel:[0,1,0] op_sel_hi:[0,1,0]
	v_add_f32_dpp v12, v12, v12 row_ror:1 row_mask:0xf bank_mask:0xf bound_ctrl:1
	v_fma_mix_f32 v133, v8, v113, v133 op_sel_hi:[0,1,0]
	v_fma_mix_f32 v133, v9, v113, v133 op_sel:[0,1,0] op_sel_hi:[0,1,0]
	v_add_f32_dpp v12, v12, v12 row_ror:2 row_mask:0xf bank_mask:0xf bound_ctrl:1
	v_pk_fma_f32 v[48:49], v[150:151], v[70:71], v[6:7] op_sel_hi:[1,0,1]
	v_pk_fma_f32 v[50:51], v[152:153], v[70:71], v[8:9] op_sel_hi:[1,0,1]
	v_add_f32_dpp v12, v12, v12 row_ror:4 row_mask:0xf bank_mask:0xf bound_ctrl:1
	v_add_f32_dpp v62, v63, v62 quad_perm:[2,3,0,1] row_mask:0xf bank_mask:0xf bound_ctrl:1
	v_add_f32_dpp v63, v65, v64 quad_perm:[2,3,0,1] row_mask:0xf bank_mask:0xf bound_ctrl:1
	v_add_f32_dpp v12, v12, v12 row_ror:8 row_mask:0xf bank_mask:0xf bound_ctrl:1
	v_pk_fma_f32 v[6:7], v[146:147], v[12:13], v[48:49] op_sel_hi:[1,0,1] neg_lo:[1,0,0] neg_hi:[1,0,0]
	v_pk_fma_f32 v[8:9], v[148:149], v[12:13], v[50:51] op_sel_hi:[1,0,1] neg_lo:[1,0,0] neg_hi:[1,0,0]
	v_fma_mix_f32 v12, v6, v158, v180 op_sel_hi:[0,1,0]
	v_fma_mix_f32 v12, v7, v158, v12 op_sel:[0,1,0] op_sel_hi:[0,1,0]
	v_fma_mix_f32 v12, v8, v159, v12 op_sel_hi:[0,1,0]
	v_fma_mix_f32 v12, v9, v159, v12 op_sel:[0,1,0] op_sel_hi:[0,1,0]
	v_fma_mix_f32 v134, v6, v144, v180 op_sel_hi:[0,1,0]
	v_fma_mix_f32 v134, v7, v144, v134 op_sel:[0,1,0] op_sel_hi:[0,1,0]
	v_add_f32_dpp v12, v12, v12 row_ror:1 row_mask:0xf bank_mask:0xf bound_ctrl:1
	v_fma_mix_f32 v134, v8, v145, v134 op_sel_hi:[0,1,0]
	v_fma_mix_f32 v134, v9, v145, v134 op_sel:[0,1,0] op_sel_hi:[0,1,0]
	v_add_f32_dpp v12, v12, v12 row_ror:2 row_mask:0xf bank_mask:0xf bound_ctrl:1
	v_pk_fma_f32 v[48:49], v[166:167], v[70:71], v[6:7] op_sel:[0,1,0]
	v_pk_fma_f32 v[50:51], v[168:169], v[70:71], v[8:9] op_sel:[0,1,0]
	v_add_f32_dpp v12, v12, v12 row_ror:4 row_mask:0xf bank_mask:0xf bound_ctrl:1
	v_cndmask_b32_e64 v65, v63, v62, s[40:41]
	v_cndmask_b32_e64 v62, v62, v63, s[40:41]
	v_add_f32_dpp v12, v12, v12 row_ror:8 row_mask:0xf bank_mask:0xf bound_ctrl:1
	v_pk_fma_f32 v[6:7], v[162:163], v[12:13], v[48:49] op_sel_hi:[1,0,1] neg_lo:[1,0,0] neg_hi:[1,0,0]
	v_pk_fma_f32 v[8:9], v[164:165], v[12:13], v[50:51] op_sel_hi:[1,0,1] neg_lo:[1,0,0] neg_hi:[1,0,0]
	v_fma_mix_f32 v12, v6, v188, v180 op_sel_hi:[0,1,0]
	v_fma_mix_f32 v12, v7, v188, v12 op_sel:[0,1,0] op_sel_hi:[0,1,0]
	v_fma_mix_f32 v12, v8, v189, v12 op_sel_hi:[0,1,0]
	v_fma_mix_f32 v12, v9, v189, v12 op_sel:[0,1,0] op_sel_hi:[0,1,0]
	v_fma_mix_f32 v135, v6, v160, v180 op_sel_hi:[0,1,0]
	v_fma_mix_f32 v135, v7, v160, v135 op_sel:[0,1,0] op_sel_hi:[0,1,0]
	v_add_f32_dpp v12, v12, v12 row_ror:1 row_mask:0xf bank_mask:0xf bound_ctrl:1
	v_fma_mix_f32 v135, v8, v161, v135 op_sel_hi:[0,1,0]
	v_fma_mix_f32 v135, v9, v161, v135 op_sel:[0,1,0] op_sel_hi:[0,1,0]
	v_add_f32_dpp v12, v12, v12 row_ror:2 row_mask:0xf bank_mask:0xf bound_ctrl:1
	v_pk_fma_f32 v[48:49], v[196:197], v[72:73], v[6:7] op_sel_hi:[1,0,1]
	v_pk_fma_f32 v[50:51], v[198:199], v[72:73], v[8:9] op_sel_hi:[1,0,1]
	v_add_f32_dpp v12, v12, v12 row_ror:4 row_mask:0xf bank_mask:0xf bound_ctrl:1
	v_add_f32_dpp v62, v62, v65 quad_perm:[1,0,3,2] row_mask:0xf bank_mask:0xf bound_ctrl:1
	v_cvt_pk_bf16_f32 v62, v62, v62
	v_add_f32_dpp v12, v12, v12 row_ror:8 row_mask:0xf bank_mask:0xf bound_ctrl:1
	v_pk_fma_f32 v[6:7], v[192:193], v[12:13], v[48:49] op_sel_hi:[1,0,1] neg_lo:[1,0,0] neg_hi:[1,0,0]
	v_pk_fma_f32 v[8:9], v[194:195], v[12:13], v[50:51] op_sel_hi:[1,0,1] neg_lo:[1,0,0] neg_hi:[1,0,0]
	s_waitcnt lgkmcnt(0)
	s_barrier
	v_xor_b32_e32 v10, 0x10000, v10
	v_xor_b32_e32 v11, 0x1000, v11
	ds_read_b128 v[66:69], v11 offset:0
	ds_read_b128 v[20:23], v10 offset:256
	ds_read_b128 v[28:31], v10 offset:768
	ds_read_b128 v[24:27], v10 offset:512
	ds_read_b128 v[36:39], v10 offset:1280
	ds_read_b128 v[44:47], v10 offset:1792
	ds_read_b128 v[40:43], v10 offset:1536
	ds_read_b128 v[88:91], v10 offset:2304
	ds_read_b128 v[96:99], v10 offset:2816
	ds_read_b128 v[92:95], v10 offset:2560
	ds_read_b128 v[110:113], v10 offset:3328
	ds_read_b128 v[106:109], v10 offset:3072
	ds_read_b128 v[118:121], v10 offset:3840
	ds_read_b128 v[114:117], v10 offset:3584
	v_fma_mix_f32 v12, v6, v204, v180 op_sel_hi:[0,1,0]
	v_fma_mix_f32 v12, v7, v204, v12 op_sel:[0,1,0] op_sel_hi:[0,1,0]
	v_fma_mix_f32 v12, v8, v205, v12 op_sel_hi:[0,1,0]
	v_fma_mix_f32 v12, v9, v205, v12 op_sel:[0,1,0] op_sel_hi:[0,1,0]
	v_fma_mix_f32 v136, v6, v190, v180 op_sel_hi:[0,1,0]
	v_fma_mix_f32 v136, v7, v190, v136 op_sel:[0,1,0] op_sel_hi:[0,1,0]
	v_add_f32_dpp v12, v12, v12 row_ror:1 row_mask:0xf bank_mask:0xf bound_ctrl:1
	v_fma_mix_f32 v136, v8, v191, v136 op_sel_hi:[0,1,0]
	v_fma_mix_f32 v136, v9, v191, v136 op_sel:[0,1,0] op_sel_hi:[0,1,0]
	v_add_f32_dpp v12, v12, v12 row_ror:2 row_mask:0xf bank_mask:0xf bound_ctrl:1
	v_pk_fma_f32 v[48:49], v[212:213], v[72:73], v[6:7] op_sel:[0,1,0]
	v_pk_fma_f32 v[50:51], v[214:215], v[72:73], v[8:9] op_sel:[0,1,0]
	v_add_f32_dpp v12, v12, v12 row_ror:4 row_mask:0xf bank_mask:0xf bound_ctrl:1
	global_store_short v[2:3], v62, off
	v_lshl_add_u64 v[2:3], v[2:3], 0, s[84:85]
	v_add_f32_dpp v12, v12, v12 row_ror:8 row_mask:0xf bank_mask:0xf bound_ctrl:1
	v_pk_fma_f32 v[6:7], v[208:209], v[12:13], v[48:49] op_sel_hi:[1,0,1] neg_lo:[1,0,0] neg_hi:[1,0,0]
	v_pk_fma_f32 v[8:9], v[210:211], v[12:13], v[50:51] op_sel_hi:[1,0,1] neg_lo:[1,0,0] neg_hi:[1,0,0]
	v_pk_mul_f32 v[6:7], v[6:7], v[200:201]
	v_pk_mul_f32 v[8:9], v[8:9], v[202:203]
	v_fma_mix_f32 v137, v6, v206, v180 op_sel_hi:[0,1,0]
	v_fma_mix_f32 v137, v7, v206, v137 op_sel:[0,1,0] op_sel_hi:[0,1,0]
	v_fma_mix_f32 v137, v8, v207, v137 op_sel_hi:[0,1,0]
	v_fma_mix_f32 v137, v9, v207, v137 op_sel:[0,1,0] op_sel_hi:[0,1,0]
	v_mov_b32_e64 v170, v2
	v_mov_b32_e64 v171, v3
	s_mov_b64 s[100:101], -1
	s_nop 0
	s_cmp_lg_u32 s28, 0x800000
	s_cbranch_scc1 .Lscan_cons_chunk
	v_add_f32_dpp v130, v130, v130 row_ror:8 row_mask:0xf bank_mask:0xc
	v_add_f32_dpp v130, v122, v122 row_ror:8 row_mask:0xf bank_mask:0x3
	v_add_f32_dpp v131, v131, v131 row_ror:8 row_mask:0xf bank_mask:0xc
	v_add_f32_dpp v131, v123, v123 row_ror:8 row_mask:0xf bank_mask:0x3
	v_add_f32_dpp v132, v132, v132 row_ror:8 row_mask:0xf bank_mask:0xc
	v_add_f32_dpp v132, v124, v124 row_ror:8 row_mask:0xf bank_mask:0x3
	v_add_f32_dpp v133, v133, v133 row_ror:8 row_mask:0xf bank_mask:0xc
	v_add_f32_dpp v133, v125, v125 row_ror:8 row_mask:0xf bank_mask:0x3
	v_add_f32_dpp v134, v134, v134 row_ror:8 row_mask:0xf bank_mask:0xc
	v_add_f32_dpp v134, v126, v126 row_ror:8 row_mask:0xf bank_mask:0x3
	v_add_f32_dpp v135, v135, v135 row_ror:8 row_mask:0xf bank_mask:0xc
	v_add_f32_dpp v135, v127, v127 row_ror:8 row_mask:0xf bank_mask:0x3
	v_add_f32_dpp v136, v136, v136 row_ror:8 row_mask:0xf bank_mask:0xc
	v_add_f32_dpp v136, v128, v128 row_ror:8 row_mask:0xf bank_mask:0x3
	v_add_f32_dpp v137, v137, v137 row_ror:8 row_mask:0xf bank_mask:0xc
	v_add_f32_dpp v137, v129, v129 row_ror:8 row_mask:0xf bank_mask:0x3
	v_add_f32_dpp v134, v134, v134 row_ror:4 row_mask:0xf bank_mask:0xa
	v_add_f32_dpp v134, v130, v130 row_ror:12 row_mask:0xf bank_mask:0x5
	v_add_f32_dpp v135, v135, v135 row_ror:4 row_mask:0xf bank_mask:0xa
	v_add_f32_dpp v135, v131, v131 row_ror:12 row_mask:0xf bank_mask:0x5
	v_add_f32_dpp v136, v136, v136 row_ror:4 row_mask:0xf bank_mask:0xa
	v_add_f32_dpp v136, v132, v132 row_ror:12 row_mask:0xf bank_mask:0x5
	v_add_f32_dpp v137, v137, v137 row_ror:4 row_mask:0xf bank_mask:0xa
	v_add_f32_dpp v137, v133, v133 row_ror:12 row_mask:0xf bank_mask:0x5
	v_cndmask_b32_e64 v62, v136, v134, s[38:39]
	v_cndmask_b32_e64 v63, v134, v136, s[38:39]
	v_cndmask_b32_e64 v64, v137, v135, s[38:39]
	v_cndmask_b32_e64 v65, v135, v137, s[38:39]
	v_add_f32_dpp v62, v63, v62 quad_perm:[2,3,0,1] row_mask:0xf bank_mask:0xf bound_ctrl:1
	s_nop 0
	v_add_f32_dpp v63, v65, v64 quad_perm:[2,3,0,1] row_mask:0xf bank_mask:0xf bound_ctrl:1
	v_cndmask_b32_e64 v65, v63, v62, s[40:41]
	v_cndmask_b32_e64 v62, v62, v63, s[40:41]
	s_nop 1
	v_add_f32_dpp v62, v62, v65 quad_perm:[1,0,3,2] row_mask:0xf bank_mask:0xf bound_ctrl:1
	v_cvt_pk_bf16_f32 v62, v62, v62
	global_store_short v[2:3], v62, off
	s_branch .LBB0_53
